# GEMM k-loops: next-stage LDS-DMA now in flight during current-stage MFMAs (vmcnt wait moved to the mid-loop barrier); plus P7 K-chunk load merge
# speedup vs baseline: 1.0924x; 1.0326x over previous
; #define MFMA(a, b, c) __builtin_amdgcn_mfma_f32_16x16x32_bf16((a), (b), (c), 0, 0, 0)
; template <int MODE, int K>
; DI void gemm_tile(const Params& p, const u16* __restrict__ A, int lda, const u16* __restrict__ Bt, int tm, int tn,
;                           char* smem) {
;     ...
;     const char* sa = smem + (k & 1) * 24576;
;     const char* sb = sa + 16384;
;     bf16x8 af[8], bfr[4];
; #pragma unroll
;     for (int i = 0; i < 8; ++i) af[i] = *(const bf16x8*)(sa + (wm * 8 + i) * 1024 + frag_off);
; #pragma unroll
;     for (int i = 0; i < 4; ++i) bfr[i] = *(const bf16x8*)(sb + (wn * 4 + i) * 1024 + frag_off);
;     __builtin_amdgcn_s_setprio(1);
; #pragma unroll
;     for (int mt = 0; mt < 8; ++mt)
; #pragma unroll
;       for (int nt = 0; nt < 4; ++nt) acc[mt][nt] = MFMA(bfr[nt], af[mt], acc[mt][nt]);
;     __builtin_amdgcn_s_setprio(0);
.LBB0_264:
	ds_read_b128 v[162:165], v188 offset:24576
	ds_read_b128 v[166:169], v188 offset:25600
	ds_read_b128 v[170:173], v188 offset:26624
	ds_read_b128 v[204:207], v188 offset:27648
	ds_read_b128 v[208:211], v188 offset:28672
	ds_read_b128 v[212:215], v188 offset:29696
	ds_read_b128 v[216:219], v188 offset:30720
	ds_read_b128 v[220:223], v189 offset:24576
	ds_read_b128 v[224:227], v190 offset:40960
	ds_read_b128 v[228:231], v190 offset:41984
	ds_read_b128 v[232:235], v190 offset:43008
	ds_read_b128 v[236:239], v190 offset:44032
	s_setprio 1
	s_waitcnt lgkmcnt(0)
	v_mfma_f32_16x16x32_bf16 v[128:131], v[224:227], v[162:165], v[128:131]
	v_mfma_f32_16x16x32_bf16 v[124:127], v[228:231], v[162:165], v[124:127]
	v_mfma_f32_16x16x32_bf16 v[120:123], v[232:235], v[162:165], v[120:123]
	v_mfma_f32_16x16x32_bf16 v[116:119], v[236:239], v[162:165], v[116:119]
	v_mfma_f32_16x16x32_bf16 v[112:115], v[224:227], v[166:169], v[112:115]
	v_mfma_f32_16x16x32_bf16 v[108:111], v[228:231], v[166:169], v[108:111]
	v_mfma_f32_16x16x32_bf16 v[104:107], v[232:235], v[166:169], v[104:107]
	v_mfma_f32_16x16x32_bf16 v[100:103], v[236:239], v[166:169], v[100:103]
	v_mfma_f32_16x16x32_bf16 v[96:99], v[224:227], v[170:173], v[96:99]
	v_mfma_f32_16x16x32_bf16 v[92:95], v[228:231], v[170:173], v[92:95]
	v_mfma_f32_16x16x32_bf16 v[88:91], v[232:235], v[170:173], v[88:91]
	v_mfma_f32_16x16x32_bf16 v[84:87], v[236:239], v[170:173], v[84:87]
	v_mfma_f32_16x16x32_bf16 v[72:75], v[224:227], v[204:207], v[72:75]
	v_mfma_f32_16x16x32_bf16 v[68:71], v[228:231], v[204:207], v[68:71]
	v_mfma_f32_16x16x32_bf16 v[80:83], v[232:235], v[204:207], v[80:83]
	v_mfma_f32_16x16x32_bf16 v[76:79], v[236:239], v[204:207], v[76:79]
	v_mfma_f32_16x16x32_bf16 v[64:67], v[224:227], v[208:211], v[64:67]
	v_mfma_f32_16x16x32_bf16 v[60:63], v[228:231], v[208:211], v[60:63]
	v_mfma_f32_16x16x32_bf16 v[56:59], v[232:235], v[208:211], v[56:59]
	v_mfma_f32_16x16x32_bf16 v[52:55], v[236:239], v[208:211], v[52:55]
	v_mfma_f32_16x16x32_bf16 v[48:51], v[224:227], v[212:215], v[48:51]
	v_mfma_f32_16x16x32_bf16 v[44:47], v[228:231], v[212:215], v[44:47]
	v_mfma_f32_16x16x32_bf16 v[40:43], v[232:235], v[212:215], v[40:43]
	v_mfma_f32_16x16x32_bf16 v[36:39], v[236:239], v[212:215], v[36:39]
	v_mfma_f32_16x16x32_bf16 v[32:35], v[224:227], v[216:219], v[32:35]
	v_mfma_f32_16x16x32_bf16 v[28:31], v[228:231], v[216:219], v[28:31]
	v_mfma_f32_16x16x32_bf16 v[24:27], v[232:235], v[216:219], v[24:27]
	v_mfma_f32_16x16x32_bf16 v[20:23], v[236:239], v[216:219], v[20:23]
	v_mfma_f32_16x16x32_bf16 v[16:19], v[224:227], v[220:223], v[16:19]
	v_mfma_f32_16x16x32_bf16 v[12:15], v[228:231], v[220:223], v[12:15]
	v_mfma_f32_16x16x32_bf16 v[4:7], v[232:235], v[220:223], v[4:7]
	v_mfma_f32_16x16x32_bf16 v[0:3], v[236:239], v[220:223], v[0:3]
	s_setprio 0
	s_add_u32 s2, s2, 0x80
	s_addc_u32 s3, s3, 0
	s_cmpk_eq_i32 s2, 0x800
	s_cbranch_scc1 .LBB0_267
; #define MFMA(a, b, c) __builtin_amdgcn_mfma_f32_16x16x32_bf16((a), (b), (c), 0, 0, 0)
; #define AS1 __attribute__((address_space(1)))
; #define AS3 __attribute__((address_space(3)))
; template <int MODE, int K>
; DI void gemm_tile(const Params& p, const u16* __restrict__ A, int lda, const u16* __restrict__ Bt, int tm, int tn,
;                           char* smem) {
;     ...
;   for (int k = 0; k < K / 32; ++k) {
;     __syncthreads();
;     if (k + 1 < K / 32) {
;       char* st = smem + ((k + 1) & 1) * 24576;
; #pragma unroll
;       for (int i = 0; i < 4; ++i)
;         __builtin_amdgcn_global_load_lds((const unsigned AS1*)(gA[i] + (k + 1) * 32), (unsigned AS3*)(st + (w * 4 + i) * 1024), 16, 0, 0);
; #pragma unroll
;       for (int i = 0; i < 2; ++i)
;         __builtin_amdgcn_global_load_lds((const unsigned AS1*)(gB[i] + (k + 1) * 32), (unsigned AS3*)(st + 16384 + (w * 2 + i) * 1024), 16, 0, 0);
;     }
;     const char* sa = smem + (k & 1) * 24576;
;     const char* sb = sa + 16384;
;     bf16x8 af[8], bfr[4];
; #pragma unroll
;     for (int i = 0; i < 8; ++i) af[i] = *(const bf16x8*)(sa + (wm * 8 + i) * 1024 + frag_off);
; #pragma unroll
;     for (int i = 0; i < 4; ++i) bfr[i] = *(const bf16x8*)(sb + (wn * 4 + i) * 1024 + frag_off);
;     __builtin_amdgcn_s_setprio(1);
; #pragma unroll
;     for (int mt = 0; mt < 8; ++mt)
; #pragma unroll
;       for (int nt = 0; nt < 4; ++nt) acc[mt][nt] = MFMA(bfr[nt], af[mt], acc[mt][nt]);
;     __builtin_amdgcn_s_setprio(0);
.LBB0_265:
	v_add_u32_e32 v166, 0x6000, v179
	v_lshl_add_u64 v[162:163], v[160:161], 0, s[2:3]
	v_readfirstlane_b32 s12, v166
	v_lshl_add_u64 v[164:165], v[162:163], 0, 64
	s_mov_b32 m0, s12
	v_add_u32_e32 v168, 0x6400, v179
	s_waitcnt vmcnt(0) lgkmcnt(0)
	s_barrier
	global_load_lds_dwordx4 v[164:165], off
	v_lshl_add_u64 v[164:165], v[158:159], 0, s[2:3]
	v_readfirstlane_b32 s12, v168
	v_lshl_add_u64 v[166:167], v[164:165], 0, 64
	s_mov_b32 m0, s12
	v_add_u32_e32 v170, 0x6800, v179
	global_load_lds_dwordx4 v[166:167], off
	v_lshl_add_u64 v[166:167], v[156:157], 0, s[2:3]
	v_readfirstlane_b32 s12, v170
	v_lshl_add_u64 v[168:169], v[166:167], 0, 64
	s_mov_b32 m0, s12
	v_add_u32_e32 v172, 0x6c00, v179
	global_load_lds_dwordx4 v[168:169], off
	v_lshl_add_u64 v[168:169], v[154:155], 0, s[2:3]
	v_readfirstlane_b32 s12, v172
	v_lshl_add_u64 v[170:171], v[168:169], 0, 64
	s_mov_b32 m0, s12
	v_add_u32_e32 v195, 0xa000, v143
	global_load_lds_dwordx4 v[170:171], off
	v_lshl_add_u64 v[170:171], v[152:153], 0, s[2:3]
	v_readfirstlane_b32 s12, v195
	v_lshl_add_u64 v[172:173], v[170:171], 0, 64
	s_mov_b32 m0, s12
	v_readfirstlane_b32 s12, v200
	global_load_lds_dwordx4 v[172:173], off
	v_lshl_add_u64 v[172:173], v[8:9], 0, s[2:3]
	v_lshl_add_u64 v[204:205], v[172:173], 0, 64
	s_mov_b32 m0, s12
	s_nop 0
	global_load_lds_dwordx4 v[204:205], off
	ds_read_b128 v[204:207], v188
	ds_read_b128 v[208:211], v188 offset:1024
	ds_read_b128 v[212:215], v188 offset:2048
	ds_read_b128 v[216:219], v188 offset:3072
	ds_read_b128 v[220:223], v188 offset:4096
	ds_read_b128 v[224:227], v188 offset:5120
	ds_read_b128 v[228:231], v188 offset:6144
	ds_read_b128 v[232:235], v189
	ds_read_b128 v[236:239], v190 offset:16384
	ds_read_b128 v[240:243], v190 offset:17408
	ds_read_b128 v[244:247], v190 offset:18432
	ds_read_b128 v[248:251], v190 offset:19456
	s_setprio 1
	s_waitcnt lgkmcnt(0)
	v_mfma_f32_16x16x32_bf16 v[128:131], v[236:239], v[204:207], v[128:131]
	v_mfma_f32_16x16x32_bf16 v[124:127], v[240:243], v[204:207], v[124:127]
	v_mfma_f32_16x16x32_bf16 v[120:123], v[244:247], v[204:207], v[120:123]
	v_mfma_f32_16x16x32_bf16 v[116:119], v[248:251], v[204:207], v[116:119]
	v_mfma_f32_16x16x32_bf16 v[112:115], v[236:239], v[208:211], v[112:115]
	v_mfma_f32_16x16x32_bf16 v[108:111], v[240:243], v[208:211], v[108:111]
	v_mfma_f32_16x16x32_bf16 v[104:107], v[244:247], v[208:211], v[104:107]
	v_mfma_f32_16x16x32_bf16 v[100:103], v[248:251], v[208:211], v[100:103]
	v_mfma_f32_16x16x32_bf16 v[96:99], v[236:239], v[212:215], v[96:99]
	v_mfma_f32_16x16x32_bf16 v[92:95], v[240:243], v[212:215], v[92:95]
	v_mfma_f32_16x16x32_bf16 v[88:91], v[244:247], v[212:215], v[88:91]
	v_mfma_f32_16x16x32_bf16 v[84:87], v[248:251], v[212:215], v[84:87]
	v_mfma_f32_16x16x32_bf16 v[72:75], v[236:239], v[216:219], v[72:75]
	v_mfma_f32_16x16x32_bf16 v[68:71], v[240:243], v[216:219], v[68:71]
	v_mfma_f32_16x16x32_bf16 v[80:83], v[244:247], v[216:219], v[80:83]
	v_mfma_f32_16x16x32_bf16 v[76:79], v[248:251], v[216:219], v[76:79]
	v_mfma_f32_16x16x32_bf16 v[64:67], v[236:239], v[220:223], v[64:67]
	v_mfma_f32_16x16x32_bf16 v[60:63], v[240:243], v[220:223], v[60:63]
	v_mfma_f32_16x16x32_bf16 v[56:59], v[244:247], v[220:223], v[56:59]
	v_mfma_f32_16x16x32_bf16 v[52:55], v[248:251], v[220:223], v[52:55]
	v_mfma_f32_16x16x32_bf16 v[48:51], v[236:239], v[224:227], v[48:51]
	v_mfma_f32_16x16x32_bf16 v[44:47], v[240:243], v[224:227], v[44:47]
	v_mfma_f32_16x16x32_bf16 v[40:43], v[244:247], v[224:227], v[40:43]
	v_mfma_f32_16x16x32_bf16 v[36:39], v[248:251], v[224:227], v[36:39]
	v_mfma_f32_16x16x32_bf16 v[32:35], v[236:239], v[228:231], v[32:35]
	v_mfma_f32_16x16x32_bf16 v[28:31], v[240:243], v[228:231], v[28:31]
	v_mfma_f32_16x16x32_bf16 v[24:27], v[244:247], v[228:231], v[24:27]
	v_mfma_f32_16x16x32_bf16 v[20:23], v[248:251], v[228:231], v[20:23]
	v_mfma_f32_16x16x32_bf16 v[16:19], v[236:239], v[232:235], v[16:19]
	v_mfma_f32_16x16x32_bf16 v[12:15], v[240:243], v[232:235], v[12:15]
	v_mfma_f32_16x16x32_bf16 v[4:7], v[244:247], v[232:235], v[4:7]
	v_mfma_f32_16x16x32_bf16 v[0:3], v[248:251], v[232:235], v[0:3]
	s_setprio 0
	s_cmpk_eq_i32 s2, 0x780
	s_waitcnt vmcnt(0)
	s_barrier
	s_cbranch_scc1 .LBB0_264
	v_readfirstlane_b32 s12, v179
	v_lshl_add_u64 v[162:163], v[162:163], 0, s[0:1]
	s_mov_b32 m0, s12
	v_readfirstlane_b32 s12, v145
	global_load_lds_dwordx4 v[162:163], off
	v_lshl_add_u64 v[162:163], v[164:165], 0, s[0:1]
	s_mov_b32 m0, s12
	v_readfirstlane_b32 s12, v194
	global_load_lds_dwordx4 v[162:163], off
	v_lshl_add_u64 v[162:163], v[166:167], 0, s[0:1]
	s_mov_b32 m0, s12
	v_readfirstlane_b32 s12, v199
	v_add_u32_e32 v164, 0x4000, v201
	global_load_lds_dwordx4 v[162:163], off
	v_lshl_add_u64 v[162:163], v[168:169], 0, s[0:1]
	s_mov_b32 m0, s12
	v_readfirstlane_b32 s12, v164
	v_add_u32_e32 v164, 0x4400, v201
	global_load_lds_dwordx4 v[162:163], off
	v_lshl_add_u64 v[162:163], v[170:171], 0, s[0:1]
	s_mov_b32 m0, s12
	v_readfirstlane_b32 s12, v164
	global_load_lds_dwordx4 v[162:163], off
	v_lshl_add_u64 v[162:163], v[172:173], 0, s[0:1]
	s_mov_b32 m0, s12
	s_nop 0
	global_load_lds_dwordx4 v[162:163], off
	s_branch .LBB0_264

; #define MFMA(a, b, c) __builtin_amdgcn_mfma_f32_16x16x32_bf16((a), (b), (c), 0, 0, 0)
; template <int MODE, int K>
; DI void gemm_tile(const Params& p, const u16* __restrict__ A, int lda, const u16* __restrict__ Bt, int tm, int tn,
;                           char* smem) {
;     ...
;     const char* sa = smem + (k & 1) * 24576;
;     const char* sb = sa + 16384;
;     bf16x8 af[8], bfr[4];
; #pragma unroll
;     for (int i = 0; i < 8; ++i) af[i] = *(const bf16x8*)(sa + (wm * 8 + i) * 1024 + frag_off);
; #pragma unroll
;     for (int i = 0; i < 4; ++i) bfr[i] = *(const bf16x8*)(sb + (wn * 4 + i) * 1024 + frag_off);
;     __builtin_amdgcn_s_setprio(1);
; #pragma unroll
;     for (int mt = 0; mt < 8; ++mt)
; #pragma unroll
;       for (int nt = 0; nt < 4; ++nt) acc[mt][nt] = MFMA(bfr[nt], af[mt], acc[mt][nt]);
;     __builtin_amdgcn_s_setprio(0);
.LBB0_287:
	ds_read_b128 v[162:165], v188 offset:24576
	ds_read_b128 v[166:169], v188 offset:25600
	ds_read_b128 v[170:173], v188 offset:26624
	ds_read_b128 v[204:207], v188 offset:27648
	ds_read_b128 v[208:211], v188 offset:28672
	ds_read_b128 v[212:215], v188 offset:29696
	ds_read_b128 v[216:219], v188 offset:30720
	ds_read_b128 v[220:223], v189 offset:24576
	ds_read_b128 v[224:227], v190 offset:40960
	ds_read_b128 v[228:231], v190 offset:41984
	ds_read_b128 v[232:235], v190 offset:43008
	ds_read_b128 v[236:239], v190 offset:44032
	s_setprio 1
	s_waitcnt lgkmcnt(0)
	v_mfma_f32_16x16x32_bf16 v[128:131], v[224:227], v[162:165], v[128:131]
	v_mfma_f32_16x16x32_bf16 v[124:127], v[228:231], v[162:165], v[124:127]
	v_mfma_f32_16x16x32_bf16 v[120:123], v[232:235], v[162:165], v[120:123]
	v_mfma_f32_16x16x32_bf16 v[116:119], v[236:239], v[162:165], v[116:119]
	v_mfma_f32_16x16x32_bf16 v[112:115], v[224:227], v[166:169], v[112:115]
	v_mfma_f32_16x16x32_bf16 v[108:111], v[228:231], v[166:169], v[108:111]
	v_mfma_f32_16x16x32_bf16 v[104:107], v[232:235], v[166:169], v[104:107]
	v_mfma_f32_16x16x32_bf16 v[100:103], v[236:239], v[166:169], v[100:103]
	v_mfma_f32_16x16x32_bf16 v[96:99], v[224:227], v[170:173], v[96:99]
	v_mfma_f32_16x16x32_bf16 v[92:95], v[228:231], v[170:173], v[92:95]
	v_mfma_f32_16x16x32_bf16 v[88:91], v[232:235], v[170:173], v[88:91]
	v_mfma_f32_16x16x32_bf16 v[84:87], v[236:239], v[170:173], v[84:87]
	v_mfma_f32_16x16x32_bf16 v[68:71], v[224:227], v[204:207], v[68:71]
	v_mfma_f32_16x16x32_bf16 v[52:55], v[228:231], v[204:207], v[52:55]
	v_mfma_f32_16x16x32_bf16 v[80:83], v[232:235], v[204:207], v[80:83]
	v_mfma_f32_16x16x32_bf16 v[76:79], v[236:239], v[204:207], v[76:79]
	v_mfma_f32_16x16x32_bf16 v[72:75], v[224:227], v[208:211], v[72:75]
	v_mfma_f32_16x16x32_bf16 v[64:67], v[228:231], v[208:211], v[64:67]
	v_mfma_f32_16x16x32_bf16 v[60:63], v[232:235], v[208:211], v[60:63]
	v_mfma_f32_16x16x32_bf16 v[56:59], v[236:239], v[208:211], v[56:59]
	v_mfma_f32_16x16x32_bf16 v[48:51], v[224:227], v[212:215], v[48:51]
	v_mfma_f32_16x16x32_bf16 v[44:47], v[228:231], v[212:215], v[44:47]
	v_mfma_f32_16x16x32_bf16 v[40:43], v[232:235], v[212:215], v[40:43]
	v_mfma_f32_16x16x32_bf16 v[36:39], v[236:239], v[212:215], v[36:39]
	v_mfma_f32_16x16x32_bf16 v[32:35], v[224:227], v[216:219], v[32:35]
	v_mfma_f32_16x16x32_bf16 v[28:31], v[228:231], v[216:219], v[28:31]
	v_mfma_f32_16x16x32_bf16 v[24:27], v[232:235], v[216:219], v[24:27]
	v_mfma_f32_16x16x32_bf16 v[20:23], v[236:239], v[216:219], v[20:23]
	v_mfma_f32_16x16x32_bf16 v[16:19], v[224:227], v[220:223], v[16:19]
	v_mfma_f32_16x16x32_bf16 v[12:15], v[228:231], v[220:223], v[12:15]
	v_mfma_f32_16x16x32_bf16 v[4:7], v[232:235], v[220:223], v[4:7]
	v_mfma_f32_16x16x32_bf16 v[0:3], v[236:239], v[220:223], v[0:3]
	s_setprio 0
	s_add_u32 s2, s2, 0x80
	s_addc_u32 s3, s3, 0
	s_cmpk_eq_i32 s2, 0x800
	s_cbranch_scc1 .LBB0_290
; #define MFMA(a, b, c) __builtin_amdgcn_mfma_f32_16x16x32_bf16((a), (b), (c), 0, 0, 0)
; #define AS1 __attribute__((address_space(1)))
; #define AS3 __attribute__((address_space(3)))
; template <int MODE, int K>
; DI void gemm_tile(const Params& p, const u16* __restrict__ A, int lda, const u16* __restrict__ Bt, int tm, int tn,
;                           char* smem) {
;     ...
;   for (int k = 0; k < K / 32; ++k) {
;     __syncthreads();
;     if (k + 1 < K / 32) {
;       char* st = smem + ((k + 1) & 1) * 24576;
; #pragma unroll
;       for (int i = 0; i < 4; ++i)
;         __builtin_amdgcn_global_load_lds((const unsigned AS1*)(gA[i] + (k + 1) * 32), (unsigned AS3*)(st + (w * 4 + i) * 1024), 16, 0, 0);
; #pragma unroll
;       for (int i = 0; i < 2; ++i)
;         __builtin_amdgcn_global_load_lds((const unsigned AS1*)(gB[i] + (k + 1) * 32), (unsigned AS3*)(st + 16384 + (w * 2 + i) * 1024), 16, 0, 0);
;     }
;     const char* sa = smem + (k & 1) * 24576;
;     const char* sb = sa + 16384;
;     bf16x8 af[8], bfr[4];
; #pragma unroll
;     for (int i = 0; i < 8; ++i) af[i] = *(const bf16x8*)(sa + (wm * 8 + i) * 1024 + frag_off);
; #pragma unroll
;     for (int i = 0; i < 4; ++i) bfr[i] = *(const bf16x8*)(sb + (wn * 4 + i) * 1024 + frag_off);
;     __builtin_amdgcn_s_setprio(1);
; #pragma unroll
;     for (int mt = 0; mt < 8; ++mt)
; #pragma unroll
;       for (int nt = 0; nt < 4; ++nt) acc[mt][nt] = MFMA(bfr[nt], af[mt], acc[mt][nt]);
;     __builtin_amdgcn_s_setprio(0);
.LBB0_288:
	v_add_u32_e32 v166, 0x6000, v179
	v_lshl_add_u64 v[162:163], v[160:161], 0, s[2:3]
	v_readfirstlane_b32 s8, v166
	v_lshl_add_u64 v[164:165], v[162:163], 0, 64
	s_mov_b32 m0, s8
	v_add_u32_e32 v168, 0x6400, v179
	s_waitcnt vmcnt(0) lgkmcnt(0)
	s_barrier
	global_load_lds_dwordx4 v[164:165], off
	v_lshl_add_u64 v[164:165], v[158:159], 0, s[2:3]
	v_readfirstlane_b32 s8, v168
	v_lshl_add_u64 v[166:167], v[164:165], 0, 64
	s_mov_b32 m0, s8
	v_add_u32_e32 v170, 0x6800, v179
	global_load_lds_dwordx4 v[166:167], off
	v_lshl_add_u64 v[166:167], v[156:157], 0, s[2:3]
	v_readfirstlane_b32 s8, v170
	v_lshl_add_u64 v[168:169], v[166:167], 0, 64
	s_mov_b32 m0, s8
	v_add_u32_e32 v172, 0x6c00, v179
	global_load_lds_dwordx4 v[168:169], off
	v_lshl_add_u64 v[168:169], v[154:155], 0, s[2:3]
	v_readfirstlane_b32 s8, v172
	v_lshl_add_u64 v[170:171], v[168:169], 0, 64
	s_mov_b32 m0, s8
	v_add_u32_e32 v195, 0xa000, v143
	global_load_lds_dwordx4 v[170:171], off
	v_lshl_add_u64 v[170:171], v[152:153], 0, s[2:3]
	v_readfirstlane_b32 s8, v195
	v_lshl_add_u64 v[172:173], v[170:171], 0, 64
	s_mov_b32 m0, s8
	v_readfirstlane_b32 s8, v202
	global_load_lds_dwordx4 v[172:173], off
	v_lshl_add_u64 v[172:173], v[8:9], 0, s[2:3]
	v_lshl_add_u64 v[204:205], v[172:173], 0, 64
	s_mov_b32 m0, s8
	s_nop 0
	global_load_lds_dwordx4 v[204:205], off
	ds_read_b128 v[204:207], v188
	ds_read_b128 v[208:211], v188 offset:1024
	ds_read_b128 v[212:215], v188 offset:2048
	ds_read_b128 v[216:219], v188 offset:3072
	ds_read_b128 v[220:223], v188 offset:4096
	ds_read_b128 v[224:227], v188 offset:5120
	ds_read_b128 v[228:231], v188 offset:6144
	ds_read_b128 v[232:235], v189
	ds_read_b128 v[236:239], v190 offset:16384
	ds_read_b128 v[240:243], v190 offset:17408
	ds_read_b128 v[244:247], v190 offset:18432
	ds_read_b128 v[248:251], v190 offset:19456
	s_setprio 1
	s_waitcnt lgkmcnt(0)
	v_mfma_f32_16x16x32_bf16 v[128:131], v[236:239], v[204:207], v[128:131]
	v_mfma_f32_16x16x32_bf16 v[124:127], v[240:243], v[204:207], v[124:127]
	v_mfma_f32_16x16x32_bf16 v[120:123], v[244:247], v[204:207], v[120:123]
	v_mfma_f32_16x16x32_bf16 v[116:119], v[248:251], v[204:207], v[116:119]
	v_mfma_f32_16x16x32_bf16 v[112:115], v[236:239], v[208:211], v[112:115]
	v_mfma_f32_16x16x32_bf16 v[108:111], v[240:243], v[208:211], v[108:111]
	v_mfma_f32_16x16x32_bf16 v[104:107], v[244:247], v[208:211], v[104:107]
	v_mfma_f32_16x16x32_bf16 v[100:103], v[248:251], v[208:211], v[100:103]
	v_mfma_f32_16x16x32_bf16 v[96:99], v[236:239], v[212:215], v[96:99]
	v_mfma_f32_16x16x32_bf16 v[92:95], v[240:243], v[212:215], v[92:95]
	v_mfma_f32_16x16x32_bf16 v[88:91], v[244:247], v[212:215], v[88:91]
	v_mfma_f32_16x16x32_bf16 v[84:87], v[248:251], v[212:215], v[84:87]
	v_mfma_f32_16x16x32_bf16 v[68:71], v[236:239], v[216:219], v[68:71]
	v_mfma_f32_16x16x32_bf16 v[52:55], v[240:243], v[216:219], v[52:55]
	v_mfma_f32_16x16x32_bf16 v[80:83], v[244:247], v[216:219], v[80:83]
	v_mfma_f32_16x16x32_bf16 v[76:79], v[248:251], v[216:219], v[76:79]
	v_mfma_f32_16x16x32_bf16 v[72:75], v[236:239], v[220:223], v[72:75]
	v_mfma_f32_16x16x32_bf16 v[64:67], v[240:243], v[220:223], v[64:67]
	v_mfma_f32_16x16x32_bf16 v[60:63], v[244:247], v[220:223], v[60:63]
	v_mfma_f32_16x16x32_bf16 v[56:59], v[248:251], v[220:223], v[56:59]
	v_mfma_f32_16x16x32_bf16 v[48:51], v[236:239], v[224:227], v[48:51]
	v_mfma_f32_16x16x32_bf16 v[44:47], v[240:243], v[224:227], v[44:47]
	v_mfma_f32_16x16x32_bf16 v[40:43], v[244:247], v[224:227], v[40:43]
	v_mfma_f32_16x16x32_bf16 v[36:39], v[248:251], v[224:227], v[36:39]
	v_mfma_f32_16x16x32_bf16 v[32:35], v[236:239], v[228:231], v[32:35]
	v_mfma_f32_16x16x32_bf16 v[28:31], v[240:243], v[228:231], v[28:31]
	v_mfma_f32_16x16x32_bf16 v[24:27], v[244:247], v[228:231], v[24:27]
	v_mfma_f32_16x16x32_bf16 v[20:23], v[248:251], v[228:231], v[20:23]
	v_mfma_f32_16x16x32_bf16 v[16:19], v[236:239], v[232:235], v[16:19]
	v_mfma_f32_16x16x32_bf16 v[12:15], v[240:243], v[232:235], v[12:15]
	v_mfma_f32_16x16x32_bf16 v[4:7], v[244:247], v[232:235], v[4:7]
	v_mfma_f32_16x16x32_bf16 v[0:3], v[248:251], v[232:235], v[0:3]
	s_setprio 0
	s_cmpk_eq_i32 s2, 0x780
	s_waitcnt vmcnt(0)
	s_barrier
	s_cbranch_scc1 .LBB0_287
	v_readfirstlane_b32 s8, v179
	v_lshl_add_u64 v[162:163], v[162:163], 0, s[0:1]
	s_mov_b32 m0, s8
	v_readfirstlane_b32 s8, v145
	global_load_lds_dwordx4 v[162:163], off
	v_lshl_add_u64 v[162:163], v[164:165], 0, s[0:1]
	s_mov_b32 m0, s8
	v_readfirstlane_b32 s8, v194
	global_load_lds_dwordx4 v[162:163], off
	v_lshl_add_u64 v[162:163], v[166:167], 0, s[0:1]
	s_mov_b32 m0, s8
	v_readfirstlane_b32 s8, v199
	global_load_lds_dwordx4 v[162:163], off
	v_lshl_add_u64 v[162:163], v[168:169], 0, s[0:1]
	s_mov_b32 m0, s8
	v_readfirstlane_b32 s8, v200
	global_load_lds_dwordx4 v[162:163], off
	v_lshl_add_u64 v[162:163], v[170:171], 0, s[0:1]
	s_mov_b32 m0, s8
	v_readfirstlane_b32 s8, v201
	global_load_lds_dwordx4 v[162:163], off
	v_lshl_add_u64 v[162:163], v[172:173], 0, s[0:1]
	s_mov_b32 m0, s8
	s_nop 0
	global_load_lds_dwordx4 v[162:163], off
	s_branch .LBB0_287

; #define MFMA(a, b, c) __builtin_amdgcn_mfma_f32_16x16x32_bf16((a), (b), (c), 0, 0, 0)
; template <int MODE, int K>
; DI void gemm_tile128(const Params& p, const u16* __restrict__ A, int lda, const u16* __restrict__ Bt, int tm, int tn,
;                           char* smem) {
;     ...
;     const char* sa = smem + (k & 1) * 32768;
;     const char* sb = sa + 16384;
; #pragma unroll
;     for (int ks = 0; ks < 2; ++ks) {
;       bf16x8 af[4], bfr[4];
; #pragma unroll
;       for (int i = 0; i < 4; ++i) {
;         af[i] = *(const bf16x8*)(sa + ((wm * 4 + i) * 2 + ks) * 1024 + frag_off);
;         bfr[i] = *(const bf16x8*)(sb + ((wn * 4 + i) * 2 + ks) * 1024 + frag_off);
;       }
;       __builtin_amdgcn_s_setprio(1);
; #pragma unroll
;       for (int mt = 0; mt < 4; ++mt)
; #pragma unroll
;         for (int nt = 0; nt < 4; ++nt) acc[mt][nt] = MFMA(bfr[nt], af[mt], acc[mt][nt]);
;       __builtin_amdgcn_s_setprio(0);
;     }
.LBB0_724:
	ds_read_b128 v[76:79], v162 offset:32768
	ds_read_b128 v[80:83], v162 offset:34816
	ds_read_b128 v[106:109], v164 offset:49152
	ds_read_b128 v[110:113], v164 offset:51200
	ds_read_b128 v[114:117], v162 offset:36864
	ds_read_b128 v[118:121], v162 offset:38912
	ds_read_b128 v[122:125], v164 offset:53248
	ds_read_b128 v[150:153], v164 offset:55296
	s_setprio 1
	s_waitcnt lgkmcnt(0)
	v_mfma_f32_16x16x32_bf16 v[0:3], v[106:109], v[76:79], v[0:3]
	v_mfma_f32_16x16x32_bf16 v[4:7], v[110:113], v[76:79], v[4:7]
	v_mfma_f32_16x16x32_bf16 v[12:15], v[122:125], v[76:79], v[12:15]
	v_mfma_f32_16x16x32_bf16 v[16:19], v[150:153], v[76:79], v[16:19]
	v_mfma_f32_16x16x32_bf16 v[20:23], v[106:109], v[80:83], v[20:23]
	v_mfma_f32_16x16x32_bf16 v[24:27], v[110:113], v[80:83], v[24:27]
	v_mfma_f32_16x16x32_bf16 v[28:31], v[122:125], v[80:83], v[28:31]
	v_mfma_f32_16x16x32_bf16 v[32:35], v[150:153], v[80:83], v[32:35]
	v_mfma_f32_16x16x32_bf16 v[76:79], v[106:109], v[114:117], v[36:39]
	v_mfma_f32_16x16x32_bf16 v[80:83], v[110:113], v[114:117], v[40:43]
	v_mfma_f32_16x16x32_bf16 v[154:157], v[122:125], v[114:117], v[44:47]
	v_mfma_f32_16x16x32_bf16 v[114:117], v[150:153], v[114:117], v[48:51]
	v_mfma_f32_16x16x32_bf16 v[106:109], v[106:109], v[118:121], v[52:55]
	v_mfma_f32_16x16x32_bf16 v[110:113], v[110:113], v[118:121], v[56:59]
	v_mfma_f32_16x16x32_bf16 v[122:125], v[122:125], v[118:121], v[60:63]
	v_mfma_f32_16x16x32_bf16 v[118:121], v[150:153], v[118:121], v[64:67]
	s_setprio 0
	ds_read_b128 v[36:39], v162 offset:33792
	ds_read_b128 v[150:153], v162 offset:35840
	ds_read_b128 v[158:161], v164 offset:50176
	ds_read_b128 v[166:169], v164 offset:52224
	ds_read_b128 v[198:201], v162 offset:37888
	ds_read_b128 v[204:207], v162 offset:39936
	ds_read_b128 v[208:211], v164 offset:54272
	ds_read_b128 v[212:215], v164 offset:56320
	s_setprio 1
	s_waitcnt lgkmcnt(5)
	v_mfma_f32_16x16x32_bf16 v[64:67], v[158:161], v[36:39], v[0:3]
	s_waitcnt lgkmcnt(4)
	v_mfma_f32_16x16x32_bf16 v[60:63], v[166:169], v[36:39], v[4:7]
	s_waitcnt lgkmcnt(1)
	v_mfma_f32_16x16x32_bf16 v[56:59], v[208:211], v[36:39], v[12:15]
	s_waitcnt lgkmcnt(0)
	v_mfma_f32_16x16x32_bf16 v[52:55], v[212:215], v[36:39], v[16:19]
	v_mfma_f32_16x16x32_bf16 v[48:51], v[158:161], v[150:153], v[20:23]
	v_mfma_f32_16x16x32_bf16 v[44:47], v[166:169], v[150:153], v[24:27]
	v_mfma_f32_16x16x32_bf16 v[40:43], v[208:211], v[150:153], v[28:31]
	v_mfma_f32_16x16x32_bf16 v[36:39], v[212:215], v[150:153], v[32:35]
	v_mfma_f32_16x16x32_bf16 v[32:35], v[158:161], v[198:201], v[76:79]
	v_mfma_f32_16x16x32_bf16 v[28:31], v[166:169], v[198:201], v[80:83]
	v_mfma_f32_16x16x32_bf16 v[24:27], v[208:211], v[198:201], v[154:157]
	v_mfma_f32_16x16x32_bf16 v[20:23], v[212:215], v[198:201], v[114:117]
	v_mfma_f32_16x16x32_bf16 v[16:19], v[158:161], v[204:207], v[106:109]
	v_mfma_f32_16x16x32_bf16 v[12:15], v[166:169], v[204:207], v[110:113]
	v_mfma_f32_16x16x32_bf16 v[4:7], v[208:211], v[204:207], v[122:125]
	v_mfma_f32_16x16x32_bf16 v[0:3], v[212:215], v[204:207], v[118:121]
	s_setprio 0
	s_add_u32 s14, s14, 0x100
	s_addc_u32 s15, s15, 0
	s_cmpk_eq_i32 s14, 0x600
	s_cbranch_scc1 .LBB0_727
; #define MFMA(a, b, c) __builtin_amdgcn_mfma_f32_16x16x32_bf16((a), (b), (c), 0, 0, 0)
; #define AS1 __attribute__((address_space(1)))
; #define AS3 __attribute__((address_space(3)))
; template <int MODE, int K>
; DI void gemm_tile128(const Params& p, const u16* __restrict__ A, int lda, const u16* __restrict__ Bt, int tm, int tn,
;                           char* smem) {
;     ...
;   for (int k = 0; k < K / 64; ++k) {
;     __syncthreads();
;     if (k + 1 < K / 64) {
;       char* st = smem + ((k + 1) & 1) * 32768;
; #pragma unroll
;       for (int i = 0; i < 4; ++i) {
;         __builtin_amdgcn_global_load_lds((const unsigned AS1*)(gA[i] + (k + 1) * 64), (unsigned AS3*)(st + (w * 4 + i) * 1024), 16, 0, 0);
;         __builtin_amdgcn_global_load_lds((const unsigned AS1*)(gB[i] + (k + 1) * 64), (unsigned AS3*)(st + 16384 + (w * 4 + i) * 1024), 16, 0, 0);
;       }
;     }
;     const char* sa = smem + (k & 1) * 32768;
;     const char* sb = sa + 16384;
; #pragma unroll
;     for (int ks = 0; ks < 2; ++ks) {
;       bf16x8 af[4], bfr[4];
; #pragma unroll
;       for (int i = 0; i < 4; ++i) {
;         af[i] = *(const bf16x8*)(sa + ((wm * 4 + i) * 2 + ks) * 1024 + frag_off);
;         bfr[i] = *(const bf16x8*)(sb + ((wn * 4 + i) * 2 + ks) * 1024 + frag_off);
;       }
;       __builtin_amdgcn_s_setprio(1);
; #pragma unroll
;       for (int mt = 0; mt < 4; ++mt)
; #pragma unroll
;         for (int nt = 0; nt < 4; ++nt) acc[mt][nt] = MFMA(bfr[nt], af[mt], acc[mt][nt]);
;       __builtin_amdgcn_s_setprio(0);
;     }
.LBB0_725:
	v_lshl_add_u64 v[76:77], v[74:75], 0, s[14:15]
	v_readfirstlane_b32 s24, v94
	v_lshl_add_u64 v[78:79], v[76:77], 0, s[0:1]
	s_mov_b32 m0, s24
	s_waitcnt vmcnt(0) lgkmcnt(0)
	s_barrier
	global_load_lds_dwordx4 v[78:79], off
	v_lshl_add_u64 v[78:79], v[72:73], 0, s[14:15]
	v_readfirstlane_b32 s24, v95
	v_lshl_add_u64 v[80:81], v[78:79], 0, s[0:1]
	s_mov_b32 m0, s24
	v_readfirstlane_b32 s24, v96
	global_load_lds_dwordx4 v[80:81], off
	v_lshl_add_u64 v[80:81], v[76:77], 0, s[2:3]
	s_mov_b32 m0, s24
	v_readfirstlane_b32 s24, v97
	global_load_lds_dwordx4 v[80:81], off
	v_lshl_add_u64 v[80:81], v[78:79], 0, s[2:3]
	s_mov_b32 m0, s24
	v_readfirstlane_b32 s24, v98
	global_load_lds_dwordx4 v[80:81], off
	v_lshl_add_u64 v[80:81], v[70:71], 0, s[14:15]
	v_lshl_add_u64 v[82:83], v[80:81], 0, s[0:1]
	s_mov_b32 m0, s24
	v_readfirstlane_b32 s24, v99
	global_load_lds_dwordx4 v[82:83], off
	v_lshl_add_u64 v[82:83], v[68:69], 0, s[14:15]
	v_lshl_add_u64 v[106:107], v[82:83], 0, s[0:1]
	s_mov_b32 m0, s24
	v_readfirstlane_b32 s24, v100
	global_load_lds_dwordx4 v[106:107], off
	v_lshl_add_u64 v[106:107], v[80:81], 0, s[2:3]
	s_mov_b32 m0, s24
	v_readfirstlane_b32 s24, v101
	global_load_lds_dwordx4 v[106:107], off
	v_lshl_add_u64 v[106:107], v[82:83], 0, s[2:3]
	s_mov_b32 m0, s24
	s_nop 0
	global_load_lds_dwordx4 v[106:107], off
	ds_read_b128 v[106:109], v162
	ds_read_b128 v[110:113], v162 offset:2048
	ds_read_b128 v[114:117], v164 offset:16384
	ds_read_b128 v[118:121], v164 offset:18432
	ds_read_b128 v[122:125], v162 offset:4096
	ds_read_b128 v[150:153], v162 offset:6144
	ds_read_b128 v[154:157], v164 offset:20480
	ds_read_b128 v[158:161], v164 offset:22528
	s_setprio 1
	s_waitcnt lgkmcnt(0)
	v_mfma_f32_16x16x32_bf16 v[64:67], v[114:117], v[106:109], v[64:67]
	v_mfma_f32_16x16x32_bf16 v[60:63], v[118:121], v[106:109], v[60:63]
	v_mfma_f32_16x16x32_bf16 v[56:59], v[154:157], v[106:109], v[56:59]
	v_mfma_f32_16x16x32_bf16 v[52:55], v[158:161], v[106:109], v[52:55]
	v_mfma_f32_16x16x32_bf16 v[48:51], v[114:117], v[110:113], v[48:51]
	v_mfma_f32_16x16x32_bf16 v[44:47], v[118:121], v[110:113], v[44:47]
	v_mfma_f32_16x16x32_bf16 v[40:43], v[154:157], v[110:113], v[40:43]
	v_mfma_f32_16x16x32_bf16 v[36:39], v[158:161], v[110:113], v[36:39]
	v_mfma_f32_16x16x32_bf16 v[106:109], v[114:117], v[122:125], v[32:35]
	v_mfma_f32_16x16x32_bf16 v[110:113], v[118:121], v[122:125], v[28:31]
	v_mfma_f32_16x16x32_bf16 v[166:169], v[154:157], v[122:125], v[24:27]
	v_mfma_f32_16x16x32_bf16 v[122:125], v[158:161], v[122:125], v[20:23]
	v_mfma_f32_16x16x32_bf16 v[114:117], v[114:117], v[150:153], v[16:19]
	v_mfma_f32_16x16x32_bf16 v[118:121], v[118:121], v[150:153], v[12:15]
	v_mfma_f32_16x16x32_bf16 v[154:157], v[154:157], v[150:153], v[4:7]
	v_mfma_f32_16x16x32_bf16 v[150:153], v[158:161], v[150:153], v[0:3]
	s_setprio 0
	ds_read_b128 v[16:19], v162 offset:1024
	ds_read_b128 v[32:35], v162 offset:3072
	ds_read_b128 v[158:161], v164 offset:17408
	ds_read_b128 v[198:201], v164 offset:19456
	ds_read_b128 v[204:207], v162 offset:5120
	ds_read_b128 v[208:211], v162 offset:7168
	ds_read_b128 v[212:215], v164 offset:21504
	ds_read_b128 v[216:219], v164 offset:23552
	s_setprio 1
	s_waitcnt lgkmcnt(5)
	v_mfma_f32_16x16x32_bf16 v[0:3], v[158:161], v[16:19], v[64:67]
	s_waitcnt lgkmcnt(4)
	v_mfma_f32_16x16x32_bf16 v[4:7], v[198:201], v[16:19], v[60:63]
	s_waitcnt lgkmcnt(1)
	v_mfma_f32_16x16x32_bf16 v[12:15], v[212:215], v[16:19], v[56:59]
	s_waitcnt lgkmcnt(0)
	v_mfma_f32_16x16x32_bf16 v[16:19], v[216:219], v[16:19], v[52:55]
	v_mfma_f32_16x16x32_bf16 v[20:23], v[158:161], v[32:35], v[48:51]
	v_mfma_f32_16x16x32_bf16 v[24:27], v[198:201], v[32:35], v[44:47]
	v_mfma_f32_16x16x32_bf16 v[28:31], v[212:215], v[32:35], v[40:43]
	v_mfma_f32_16x16x32_bf16 v[32:35], v[216:219], v[32:35], v[36:39]
	v_mfma_f32_16x16x32_bf16 v[36:39], v[158:161], v[204:207], v[106:109]
	v_mfma_f32_16x16x32_bf16 v[40:43], v[198:201], v[204:207], v[110:113]
	v_mfma_f32_16x16x32_bf16 v[44:47], v[212:215], v[204:207], v[166:169]
	v_mfma_f32_16x16x32_bf16 v[48:51], v[216:219], v[204:207], v[122:125]
	v_mfma_f32_16x16x32_bf16 v[52:55], v[158:161], v[208:211], v[114:117]
	v_mfma_f32_16x16x32_bf16 v[56:59], v[198:201], v[208:211], v[118:121]
	v_mfma_f32_16x16x32_bf16 v[60:63], v[212:215], v[208:211], v[154:157]
	v_mfma_f32_16x16x32_bf16 v[64:67], v[216:219], v[208:211], v[150:153]
	s_setprio 0
	s_cmpk_eq_i32 s14, 0x500
	s_waitcnt vmcnt(0)
	s_barrier
	s_cbranch_scc1 .LBB0_724
	v_readfirstlane_b32 s24, v179
	v_lshl_add_u64 v[106:107], v[76:77], 0, s[10:11]
	s_mov_b32 m0, s24
	v_readfirstlane_b32 s24, v86
	global_load_lds_dwordx4 v[106:107], off
	v_lshl_add_u64 v[106:107], v[78:79], 0, s[10:11]
	s_mov_b32 m0, s24
	v_readfirstlane_b32 s24, v87
	global_load_lds_dwordx4 v[106:107], off
	v_lshl_add_u64 v[76:77], v[76:77], 0, s[12:13]
	s_mov_b32 m0, s24
	v_readfirstlane_b32 s24, v88
	global_load_lds_dwordx4 v[76:77], off
	v_lshl_add_u64 v[76:77], v[78:79], 0, s[12:13]
	s_mov_b32 m0, s24
	v_readfirstlane_b32 s24, v89
	global_load_lds_dwordx4 v[76:77], off
	v_lshl_add_u64 v[76:77], v[80:81], 0, s[10:11]
	s_mov_b32 m0, s24
	v_readfirstlane_b32 s24, v90
	global_load_lds_dwordx4 v[76:77], off
	v_lshl_add_u64 v[76:77], v[82:83], 0, s[10:11]
	s_mov_b32 m0, s24
	v_readfirstlane_b32 s24, v91
	global_load_lds_dwordx4 v[76:77], off
	v_lshl_add_u64 v[76:77], v[80:81], 0, s[12:13]
	s_mov_b32 m0, s24
	v_readfirstlane_b32 s24, v93
	global_load_lds_dwordx4 v[76:77], off
	v_lshl_add_u64 v[76:77], v[82:83], 0, s[12:13]
	s_mov_b32 m0, s24
	s_nop 0
	global_load_lds_dwordx4 v[76:77], off
	s_branch .LBB0_724

; #define MFMA(a, b, c) __builtin_amdgcn_mfma_f32_16x16x32_bf16((a), (b), (c), 0, 0, 0)
; template <int MODE, int K>
; DI void gemm_tile128(const Params& p, const u16* __restrict__ A, int lda, const u16* __restrict__ Bt, int tm, int tn,
;                           char* smem) {
;     ...
;     const char* sa = smem + (k & 1) * 32768;
;     const char* sb = sa + 16384;
; #pragma unroll
;     for (int ks = 0; ks < 2; ++ks) {
;       bf16x8 af[4], bfr[4];
; #pragma unroll
;       for (int i = 0; i < 4; ++i) {
;         af[i] = *(const bf16x8*)(sa + ((wm * 4 + i) * 2 + ks) * 1024 + frag_off);
;         bfr[i] = *(const bf16x8*)(sb + ((wn * 4 + i) * 2 + ks) * 1024 + frag_off);
;       }
;       __builtin_amdgcn_s_setprio(1);
; #pragma unroll
;       for (int mt = 0; mt < 4; ++mt)
; #pragma unroll
;         for (int nt = 0; nt < 4; ++nt) acc[mt][nt] = MFMA(bfr[nt], af[mt], acc[mt][nt]);
;       __builtin_amdgcn_s_setprio(0);
;     }
.LBB0_786:
	ds_read_b128 v[74:77], v162 offset:32768
	ds_read_b128 v[78:81], v162 offset:34816
	ds_read_b128 v[104:107], v164 offset:49152
	ds_read_b128 v[108:111], v164 offset:51200
	ds_read_b128 v[112:115], v162 offset:36864
	ds_read_b128 v[116:119], v162 offset:38912
	ds_read_b128 v[120:123], v164 offset:53248
	ds_read_b128 v[124:127], v164 offset:55296
	s_setprio 1
	s_waitcnt lgkmcnt(0)
	v_mfma_f32_16x16x32_bf16 v[0:3], v[104:107], v[74:77], v[0:3]
	v_mfma_f32_16x16x32_bf16 v[4:7], v[108:111], v[74:77], v[4:7]
	v_mfma_f32_16x16x32_bf16 v[12:15], v[120:123], v[74:77], v[12:15]
	v_mfma_f32_16x16x32_bf16 v[16:19], v[124:127], v[74:77], v[16:19]
	v_mfma_f32_16x16x32_bf16 v[20:23], v[104:107], v[78:81], v[20:23]
	v_mfma_f32_16x16x32_bf16 v[24:27], v[108:111], v[78:81], v[24:27]
	v_mfma_f32_16x16x32_bf16 v[28:31], v[120:123], v[78:81], v[28:31]
	v_mfma_f32_16x16x32_bf16 v[32:35], v[124:127], v[78:81], v[32:35]
	v_mfma_f32_16x16x32_bf16 v[74:77], v[104:107], v[112:115], v[36:39]
	v_mfma_f32_16x16x32_bf16 v[78:81], v[108:111], v[112:115], v[40:43]
	v_mfma_f32_16x16x32_bf16 v[150:153], v[120:123], v[112:115], v[44:47]
	v_mfma_f32_16x16x32_bf16 v[112:115], v[124:127], v[112:115], v[48:51]
	v_mfma_f32_16x16x32_bf16 v[104:107], v[104:107], v[116:119], v[52:55]
	v_mfma_f32_16x16x32_bf16 v[108:111], v[108:111], v[116:119], v[56:59]
	v_mfma_f32_16x16x32_bf16 v[120:123], v[120:123], v[116:119], v[60:63]
	v_mfma_f32_16x16x32_bf16 v[116:119], v[124:127], v[116:119], v[64:67]
	s_setprio 0
	ds_read_b128 v[36:39], v162 offset:33792
	ds_read_b128 v[124:127], v162 offset:35840
	ds_read_b128 v[154:157], v164 offset:50176
	ds_read_b128 v[158:161], v164 offset:52224
	ds_read_b128 v[166:169], v162 offset:37888
	ds_read_b128 v[198:201], v162 offset:39936
	ds_read_b128 v[204:207], v164 offset:54272
	ds_read_b128 v[208:211], v164 offset:56320
	s_setprio 1
	s_waitcnt lgkmcnt(5)
	v_mfma_f32_16x16x32_bf16 v[64:67], v[154:157], v[36:39], v[0:3]
	s_waitcnt lgkmcnt(4)
	v_mfma_f32_16x16x32_bf16 v[60:63], v[158:161], v[36:39], v[4:7]
	s_waitcnt lgkmcnt(1)
	v_mfma_f32_16x16x32_bf16 v[56:59], v[204:207], v[36:39], v[12:15]
	s_waitcnt lgkmcnt(0)
	v_mfma_f32_16x16x32_bf16 v[52:55], v[208:211], v[36:39], v[16:19]
	v_mfma_f32_16x16x32_bf16 v[48:51], v[154:157], v[124:127], v[20:23]
	v_mfma_f32_16x16x32_bf16 v[44:47], v[158:161], v[124:127], v[24:27]
	v_mfma_f32_16x16x32_bf16 v[40:43], v[204:207], v[124:127], v[28:31]
	v_mfma_f32_16x16x32_bf16 v[36:39], v[208:211], v[124:127], v[32:35]
	v_mfma_f32_16x16x32_bf16 v[20:23], v[154:157], v[166:169], v[74:77]
	v_mfma_f32_16x16x32_bf16 v[24:27], v[158:161], v[166:169], v[78:81]
	v_mfma_f32_16x16x32_bf16 v[28:31], v[204:207], v[166:169], v[150:153]
	v_mfma_f32_16x16x32_bf16 v[32:35], v[208:211], v[166:169], v[112:115]
	v_mfma_f32_16x16x32_bf16 v[0:3], v[154:157], v[198:201], v[104:107]
	v_mfma_f32_16x16x32_bf16 v[4:7], v[158:161], v[198:201], v[108:111]
	v_mfma_f32_16x16x32_bf16 v[12:15], v[204:207], v[198:201], v[120:123]
	v_mfma_f32_16x16x32_bf16 v[16:19], v[208:211], v[198:201], v[116:119]
	s_setprio 0
	s_add_u32 s14, s14, 0x100
	s_addc_u32 s15, s15, 0
	s_cmpk_lg_i32 s14, 0x800
	s_cbranch_scc0 .LBB0_780
; #define MFMA(a, b, c) __builtin_amdgcn_mfma_f32_16x16x32_bf16((a), (b), (c), 0, 0, 0)
; #define AS1 __attribute__((address_space(1)))
; #define AS3 __attribute__((address_space(3)))
; template <int MODE, int K>
; DI void gemm_tile128(const Params& p, const u16* __restrict__ A, int lda, const u16* __restrict__ Bt, int tm, int tn,
;                           char* smem) {
;     ...
;   for (int k = 0; k < K / 64; ++k) {
;     __syncthreads();
;     if (k + 1 < K / 64) {
;       char* st = smem + ((k + 1) & 1) * 32768;
; #pragma unroll
;       for (int i = 0; i < 4; ++i) {
;         __builtin_amdgcn_global_load_lds((const unsigned AS1*)(gA[i] + (k + 1) * 64), (unsigned AS3*)(st + (w * 4 + i) * 1024), 16, 0, 0);
;         __builtin_amdgcn_global_load_lds((const unsigned AS1*)(gB[i] + (k + 1) * 64), (unsigned AS3*)(st + 16384 + (w * 4 + i) * 1024), 16, 0, 0);
;       }
;     }
;     const char* sa = smem + (k & 1) * 32768;
;     const char* sb = sa + 16384;
; #pragma unroll
;     for (int ks = 0; ks < 2; ++ks) {
;       bf16x8 af[4], bfr[4];
; #pragma unroll
;       for (int i = 0; i < 4; ++i) {
;         af[i] = *(const bf16x8*)(sa + ((wm * 4 + i) * 2 + ks) * 1024 + frag_off);
;         bfr[i] = *(const bf16x8*)(sb + ((wn * 4 + i) * 2 + ks) * 1024 + frag_off);
;       }
;       __builtin_amdgcn_s_setprio(1);
; #pragma unroll
;       for (int mt = 0; mt < 4; ++mt)
; #pragma unroll
;         for (int nt = 0; nt < 4; ++nt) acc[mt][nt] = MFMA(bfr[nt], af[mt], acc[mt][nt]);
;       __builtin_amdgcn_s_setprio(0);
;     }
.LBB0_787:
	v_lshl_add_u64 v[74:75], v[72:73], 0, s[14:15]
	v_readfirstlane_b32 s23, v91
	v_lshl_add_u64 v[76:77], v[74:75], 0, s[0:1]
	s_mov_b32 m0, s23
	s_waitcnt vmcnt(0) lgkmcnt(0)
	s_barrier
	global_load_lds_dwordx4 v[76:77], off
	v_lshl_add_u64 v[76:77], v[70:71], 0, s[14:15]
	v_readfirstlane_b32 s23, v93
	v_lshl_add_u64 v[78:79], v[76:77], 0, s[0:1]
	s_mov_b32 m0, s23
	v_readfirstlane_b32 s23, v94
	global_load_lds_dwordx4 v[78:79], off
	v_lshl_add_u64 v[78:79], v[74:75], 0, s[2:3]
	s_mov_b32 m0, s23
	v_readfirstlane_b32 s23, v95
	global_load_lds_dwordx4 v[78:79], off
	v_lshl_add_u64 v[78:79], v[76:77], 0, s[2:3]
	s_mov_b32 m0, s23
	v_readfirstlane_b32 s23, v96
	global_load_lds_dwordx4 v[78:79], off
	v_lshl_add_u64 v[78:79], v[68:69], 0, s[14:15]
	v_lshl_add_u64 v[80:81], v[78:79], 0, s[0:1]
	s_mov_b32 m0, s23
	v_readfirstlane_b32 s23, v97
	global_load_lds_dwordx4 v[80:81], off
	v_lshl_add_u64 v[80:81], v[8:9], 0, s[14:15]
	v_lshl_add_u64 v[104:105], v[80:81], 0, s[0:1]
	s_mov_b32 m0, s23
	v_readfirstlane_b32 s23, v98
	global_load_lds_dwordx4 v[104:105], off
	v_lshl_add_u64 v[104:105], v[78:79], 0, s[2:3]
	s_mov_b32 m0, s23
	v_readfirstlane_b32 s23, v99
	global_load_lds_dwordx4 v[104:105], off
	v_lshl_add_u64 v[104:105], v[80:81], 0, s[2:3]
	s_mov_b32 m0, s23
	s_nop 0
	global_load_lds_dwordx4 v[104:105], off
	ds_read_b128 v[104:107], v162
	ds_read_b128 v[108:111], v162 offset:2048
	ds_read_b128 v[112:115], v164 offset:16384
	ds_read_b128 v[116:119], v164 offset:18432
	ds_read_b128 v[120:123], v162 offset:4096
	ds_read_b128 v[124:127], v162 offset:6144
	ds_read_b128 v[150:153], v164 offset:20480
	ds_read_b128 v[154:157], v164 offset:22528
	s_setprio 1
	s_waitcnt lgkmcnt(0)
	v_mfma_f32_16x16x32_bf16 v[64:67], v[112:115], v[104:107], v[64:67]
	v_mfma_f32_16x16x32_bf16 v[60:63], v[116:119], v[104:107], v[60:63]
	v_mfma_f32_16x16x32_bf16 v[56:59], v[150:153], v[104:107], v[56:59]
	v_mfma_f32_16x16x32_bf16 v[52:55], v[154:157], v[104:107], v[52:55]
	v_mfma_f32_16x16x32_bf16 v[48:51], v[112:115], v[108:111], v[48:51]
	v_mfma_f32_16x16x32_bf16 v[44:47], v[116:119], v[108:111], v[44:47]
	v_mfma_f32_16x16x32_bf16 v[40:43], v[150:153], v[108:111], v[40:43]
	v_mfma_f32_16x16x32_bf16 v[36:39], v[154:157], v[108:111], v[36:39]
	v_mfma_f32_16x16x32_bf16 v[104:107], v[112:115], v[120:123], v[20:23]
	v_mfma_f32_16x16x32_bf16 v[108:111], v[116:119], v[120:123], v[24:27]
	v_mfma_f32_16x16x32_bf16 v[158:161], v[150:153], v[120:123], v[28:31]
	v_mfma_f32_16x16x32_bf16 v[120:123], v[154:157], v[120:123], v[32:35]
	v_mfma_f32_16x16x32_bf16 v[112:115], v[112:115], v[124:127], v[0:3]
	v_mfma_f32_16x16x32_bf16 v[116:119], v[116:119], v[124:127], v[4:7]
	v_mfma_f32_16x16x32_bf16 v[150:153], v[150:153], v[124:127], v[12:15]
	v_mfma_f32_16x16x32_bf16 v[124:127], v[154:157], v[124:127], v[16:19]
	s_setprio 0
	s_nop 1
	ds_read_b128 v[16:19], v162 offset:1024
	ds_read_b128 v[32:35], v162 offset:3072
	ds_read_b128 v[154:157], v164 offset:17408
	ds_read_b128 v[166:169], v164 offset:19456
	ds_read_b128 v[198:201], v162 offset:5120
	ds_read_b128 v[204:207], v162 offset:7168
	ds_read_b128 v[208:211], v164 offset:21504
	ds_read_b128 v[212:215], v164 offset:23552
	s_setprio 1
	s_waitcnt lgkmcnt(5)
	v_mfma_f32_16x16x32_bf16 v[0:3], v[154:157], v[16:19], v[64:67]
	s_waitcnt lgkmcnt(4)
	v_mfma_f32_16x16x32_bf16 v[4:7], v[166:169], v[16:19], v[60:63]
	s_waitcnt lgkmcnt(1)
	v_mfma_f32_16x16x32_bf16 v[12:15], v[208:211], v[16:19], v[56:59]
	s_waitcnt lgkmcnt(0)
	v_mfma_f32_16x16x32_bf16 v[16:19], v[212:215], v[16:19], v[52:55]
	v_mfma_f32_16x16x32_bf16 v[20:23], v[154:157], v[32:35], v[48:51]
	v_mfma_f32_16x16x32_bf16 v[24:27], v[166:169], v[32:35], v[44:47]
	v_mfma_f32_16x16x32_bf16 v[28:31], v[208:211], v[32:35], v[40:43]
	v_mfma_f32_16x16x32_bf16 v[32:35], v[212:215], v[32:35], v[36:39]
	v_mfma_f32_16x16x32_bf16 v[36:39], v[154:157], v[198:201], v[104:107]
	v_mfma_f32_16x16x32_bf16 v[40:43], v[166:169], v[198:201], v[108:111]
	v_mfma_f32_16x16x32_bf16 v[44:47], v[208:211], v[198:201], v[158:161]
	v_mfma_f32_16x16x32_bf16 v[48:51], v[212:215], v[198:201], v[120:123]
	v_mfma_f32_16x16x32_bf16 v[52:55], v[154:157], v[204:207], v[112:115]
	v_mfma_f32_16x16x32_bf16 v[56:59], v[166:169], v[204:207], v[116:119]
	v_mfma_f32_16x16x32_bf16 v[60:63], v[208:211], v[204:207], v[150:153]
	v_mfma_f32_16x16x32_bf16 v[64:67], v[212:215], v[204:207], v[124:127]
	s_setprio 0
	s_cmpk_eq_i32 s14, 0x700
	s_waitcnt vmcnt(0)
	s_barrier
	s_cbranch_scc1 .LBB0_786
	v_readfirstlane_b32 s23, v179
	v_lshl_add_u64 v[104:105], v[74:75], 0, s[10:11]
	s_mov_b32 m0, s23
	v_readfirstlane_b32 s23, v84
	global_load_lds_dwordx4 v[104:105], off
	v_lshl_add_u64 v[104:105], v[76:77], 0, s[10:11]
	s_mov_b32 m0, s23
	v_readfirstlane_b32 s23, v85
	global_load_lds_dwordx4 v[104:105], off
	v_lshl_add_u64 v[74:75], v[74:75], 0, s[12:13]
	s_mov_b32 m0, s23
	v_readfirstlane_b32 s23, v86
	global_load_lds_dwordx4 v[74:75], off
	v_lshl_add_u64 v[74:75], v[76:77], 0, s[12:13]
	s_mov_b32 m0, s23
	v_readfirstlane_b32 s23, v87
	global_load_lds_dwordx4 v[74:75], off
	v_lshl_add_u64 v[74:75], v[78:79], 0, s[10:11]
	s_mov_b32 m0, s23
	v_readfirstlane_b32 s23, v88
	global_load_lds_dwordx4 v[74:75], off
	v_lshl_add_u64 v[74:75], v[80:81], 0, s[10:11]
	s_mov_b32 m0, s23
	v_readfirstlane_b32 s23, v89
	global_load_lds_dwordx4 v[74:75], off
	v_lshl_add_u64 v[74:75], v[78:79], 0, s[12:13]
	s_mov_b32 m0, s23
	v_readfirstlane_b32 s23, v90
	global_load_lds_dwordx4 v[74:75], off
	v_lshl_add_u64 v[74:75], v[80:81], 0, s[12:13]
	s_mov_b32 m0, s23
	s_nop 0
	global_load_lds_dwordx4 v[74:75], off
	s_branch .LBB0_786

; #define MFMA(a, b, c) __builtin_amdgcn_mfma_f32_16x16x32_bf16((a), (b), (c), 0, 0, 0)
; DI void mem_attn_prompt_block(const Params& p, int item, char* smem) {
;     ...
;   bf16x8 qf[8];
; #pragma unroll
;   for (int ks = 0; ks < 8; ++ks) qf[ks] = *(const bf16x8*)&G(p.qb)[(size_t)(row0 + r) * 1024 + h * 256 + ks * 32 + kg * 8];
;   f32x4 st[16];
;   const u16* kbp = G(p.Kb) + (size_t)bh * 65536;
; #pragma unroll
;   for (int c = 0; c < 4; ++c) {
;     __syncthreads();
; #pragma unroll
;     for (int i2 = 0; i2 < 2; ++i2) {
; #pragma unroll
;       for (int i = i2 * 4; i < i2 * 4 + 4; ++i) {
;         const int idx = tid + 256 * i, row = idx >> 5, seg = idx & 31;
;         *(bf16x8*)&sK[row * 264 + seg * 8] = *(gb8p)((gu16p)kbp + (size_t)(c * 64 + row) * 256 + seg * 8);
;       }
;       __builtin_amdgcn_sched_barrier(0);
;     }
;     __syncthreads();
; #pragma unroll
;     for (int m4 = 0; m4 < 4; ++m4) {
;       f32x4 a = (f32x4){0.f, 0.f, 0.f, 0.f};
; #pragma unroll
;       for (int ks = 0; ks < 8; ++ks) {
;         bf16x8 kf = *(const bf16x8*)&sK[(m4 * 16 + r) * 264 + ks * 32 + kg * 8];
;         a = MFMA(kf, qf[ks], a);
;       }
;       st[c * 4 + m4] = a;
;       __builtin_amdgcn_sched_barrier(0);
;     }
;   }
.LBB0_887:
	s_cmp_gt_i32 s48, 31
	s_mov_b64 s[24:25], -1
	s_cbranch_scc0 .LBB0_891
	s_sub_i32 s0, s48, 32
	s_lshl_b32 s25, s0, 4
	ds_read_b64 v[0:1], v126
	ds_read_b64 v[4:5], v127
	s_and_b32 s24, s48, 3
	s_and_b32 s25, s25, 0x7fc0
	v_add_lshl_u32 v2, v120, s25, 10
	s_lshl_b32 s25, s24, 8
	v_or3_b32 v2, v2, s25, v172
	v_lshlrev_b32_e32 v2, 1, v2
	v_mov_b32_e32 v3, v95
	s_lshr_b32 s0, s0, 7
	s_waitcnt lgkmcnt(0)
	v_lshl_add_u64 v[0:1], v[0:1], 0, v[2:3]
	s_and_b32 s0, s0, 12
	flat_load_dwordx4 v[44:47], v[0:1]
	flat_load_dwordx4 v[40:43], v[0:1] offset:64
	flat_load_dwordx4 v[36:39], v[0:1] offset:128
	flat_load_dwordx4 v[32:35], v[0:1] offset:192
	flat_load_dwordx4 v[28:31], v[0:1] offset:256
	flat_load_dwordx4 v[24:27], v[0:1] offset:320
	flat_load_dwordx4 v[16:19], v[0:1] offset:384
	flat_load_dwordx4 v[20:23], v[0:1] offset:448
	s_or_b32 s0, s0, s24
	s_lshl_b32 s0, s0, 17
	v_lshl_add_u64 v[0:1], v[4:5], 0, s[0:1]
	v_mov_b32_e32 v115, v95
	v_lshl_add_u64 v[48:49], v[0:1], 0, v[114:115]
	v_lshl_add_u64 v[80:81], v[48:49], 0, v[96:97]
	v_lshl_add_u64 v[90:91], v[48:49], 0, v[100:101]
	s_waitcnt lgkmcnt(0)
	s_barrier
	v_lshl_add_u64 v[118:119], v[48:49], 0, v[98:99]
	global_load_dwordx4 v[0:3], v[80:81], off
	global_load_dwordx4 v[4:7], v[118:119], off
	v_lshl_add_u64 v[86:87], v[48:49], 0, v[102:103]
	global_load_dwordx4 v[8:11], v[90:91], off
	global_load_dwordx4 v[12:15], v[86:87], off
	s_and_b32 s24, s27, 0x7fc0
	v_add_u32_e32 v50, s24, v120
	s_and_b32 s25, s47, 3
	v_lshl_or_b32 v50, v50, 11, v125
	v_lshl_or_b32 v50, s25, 9, v50
	v_or_b32_e32 v94, 0x60, v50
	v_lshl_add_u64 v[204:205], v[48:49], 0, v[104:105]
	v_lshl_add_u64 v[84:85], v[48:49], 0, v[108:109]
	v_lshl_add_u64 v[88:89], v[48:49], 0, v[106:107]
	global_load_dwordx4 v[204:207], v[204:205], off
	s_nop 0
	global_load_dwordx4 v[208:211], v[88:89], off
	v_lshl_add_u64 v[82:83], v[48:49], 0, v[110:111]
	global_load_dwordx4 v[212:215], v[84:85], off
	global_load_dwordx4 v[216:219], v[82:83], off
	s_waitcnt vmcnt(4)
	ds_write_b128 v130, v[0:3]
	ds_write_b128 v131, v[4:7]
	ds_write_b128 v137, v[8:11]
	ds_write_b128 v142, v[12:15]
	s_waitcnt vmcnt(3)
	ds_write_b128 v130, v[204:207] offset:16896
	s_waitcnt vmcnt(2)
	ds_write_b128 v145, v[208:211]
	s_waitcnt vmcnt(1)
	ds_write_b128 v146, v[212:215]
	s_waitcnt vmcnt(0)
	ds_write_b128 v147, v[216:219]
	s_waitcnt lgkmcnt(0)
	s_barrier
	ds_read_b128 v[0:3], v121
	ds_read_b128 v[4:7], v121 offset:64
	s_waitcnt lgkmcnt(1)
	v_mfma_f32_16x16x32_bf16 v[0:3], v[0:3], v[44:47], 0
	ds_read_b128 v[8:11], v121 offset:128
	s_waitcnt lgkmcnt(1)
	v_mfma_f32_16x16x32_bf16 v[0:3], v[4:7], v[40:43], v[0:3]
	ds_read_b128 v[4:7], v121 offset:192
	s_waitcnt lgkmcnt(1)
	v_mfma_f32_16x16x32_bf16 v[0:3], v[8:11], v[36:39], v[0:3]
	ds_read_b128 v[8:11], v121 offset:256
	s_waitcnt lgkmcnt(1)
	v_mfma_f32_16x16x32_bf16 v[0:3], v[4:7], v[32:35], v[0:3]
	ds_read_b128 v[4:7], v121 offset:320
	s_waitcnt lgkmcnt(1)
	v_mfma_f32_16x16x32_bf16 v[0:3], v[8:11], v[28:31], v[0:3]
	ds_read_b128 v[8:11], v121 offset:384
	s_waitcnt lgkmcnt(1)
	v_mfma_f32_16x16x32_bf16 v[0:3], v[4:7], v[24:27], v[0:3]
	ds_read_b128 v[4:7], v121 offset:448
	s_waitcnt lgkmcnt(1)
	v_mfma_f32_16x16x32_bf16 v[0:3], v[8:11], v[16:19], v[0:3]
	s_waitcnt lgkmcnt(0)
	v_mfma_f32_16x16x32_bf16 v[0:3], v[4:7], v[20:23], v[0:3]
	ds_read_b128 v[4:7], v121 offset:8448
	ds_read_b128 v[8:11], v121 offset:8512
	ds_read_b128 v[12:15], v121 offset:8576
	s_waitcnt lgkmcnt(2)
	v_mfma_f32_16x16x32_bf16 v[4:7], v[4:7], v[44:47], 0
	s_waitcnt lgkmcnt(1)
	v_mfma_f32_16x16x32_bf16 v[4:7], v[8:11], v[40:43], v[4:7]
	ds_read_b128 v[8:11], v121 offset:8640
	s_waitcnt lgkmcnt(1)
	v_mfma_f32_16x16x32_bf16 v[4:7], v[12:15], v[36:39], v[4:7]
	ds_read_b128 v[12:15], v121 offset:8704
	s_waitcnt lgkmcnt(1)
	v_mfma_f32_16x16x32_bf16 v[4:7], v[8:11], v[32:35], v[4:7]
	ds_read_b128 v[8:11], v121 offset:8768
	s_waitcnt lgkmcnt(1)
	v_mfma_f32_16x16x32_bf16 v[4:7], v[12:15], v[28:31], v[4:7]
	ds_read_b128 v[12:15], v121 offset:8832
	s_waitcnt lgkmcnt(1)
	v_mfma_f32_16x16x32_bf16 v[4:7], v[8:11], v[24:27], v[4:7]
	ds_read_b128 v[8:11], v121 offset:8896
	s_waitcnt lgkmcnt(1)
	v_mfma_f32_16x16x32_bf16 v[4:7], v[12:15], v[16:19], v[4:7]
	s_waitcnt lgkmcnt(0)
	v_mfma_f32_16x16x32_bf16 v[4:7], v[8:11], v[20:23], v[4:7]
	ds_read_b128 v[8:11], v121 offset:16896
	ds_read_b128 v[12:15], v121 offset:16960
	ds_read_b128 v[48:51], v121 offset:17024
	s_waitcnt lgkmcnt(2)
	v_mfma_f32_16x16x32_bf16 v[8:11], v[8:11], v[44:47], 0
	s_waitcnt lgkmcnt(1)
	v_mfma_f32_16x16x32_bf16 v[8:11], v[12:15], v[40:43], v[8:11]
	ds_read_b128 v[12:15], v121 offset:17088
	s_waitcnt lgkmcnt(1)
	v_mfma_f32_16x16x32_bf16 v[8:11], v[48:51], v[36:39], v[8:11]
	ds_read_b128 v[48:51], v121 offset:17152
	s_waitcnt lgkmcnt(1)
	v_mfma_f32_16x16x32_bf16 v[8:11], v[12:15], v[32:35], v[8:11]
	ds_read_b128 v[12:15], v121 offset:17216
	s_waitcnt lgkmcnt(1)
	v_mfma_f32_16x16x32_bf16 v[8:11], v[48:51], v[28:31], v[8:11]
	ds_read_b128 v[48:51], v121 offset:17280
	s_waitcnt lgkmcnt(1)
	v_mfma_f32_16x16x32_bf16 v[8:11], v[12:15], v[24:27], v[8:11]
	ds_read_b128 v[12:15], v121 offset:17344
	s_waitcnt lgkmcnt(1)
	v_mfma_f32_16x16x32_bf16 v[8:11], v[48:51], v[16:19], v[8:11]
	s_waitcnt lgkmcnt(0)
	v_mfma_f32_16x16x32_bf16 v[8:11], v[12:15], v[20:23], v[8:11]
	ds_read_b128 v[12:15], v121 offset:25344
	ds_read_b128 v[48:51], v121 offset:25408
	ds_read_b128 v[52:55], v121 offset:25472
	s_waitcnt lgkmcnt(2)
	v_mfma_f32_16x16x32_bf16 v[12:15], v[12:15], v[44:47], 0
	s_waitcnt lgkmcnt(1)
	v_mfma_f32_16x16x32_bf16 v[12:15], v[48:51], v[40:43], v[12:15]
	ds_read_b128 v[48:51], v121 offset:25536
	s_waitcnt lgkmcnt(1)
	v_mfma_f32_16x16x32_bf16 v[12:15], v[52:55], v[36:39], v[12:15]
	ds_read_b128 v[52:55], v121 offset:25600
	s_waitcnt lgkmcnt(1)
	v_mfma_f32_16x16x32_bf16 v[12:15], v[48:51], v[32:35], v[12:15]
	ds_read_b128 v[48:51], v121 offset:25664
	s_waitcnt lgkmcnt(1)
	v_mfma_f32_16x16x32_bf16 v[12:15], v[52:55], v[28:31], v[12:15]
	ds_read_b128 v[52:55], v121 offset:25728
	s_waitcnt lgkmcnt(1)
	v_mfma_f32_16x16x32_bf16 v[12:15], v[48:51], v[24:27], v[12:15]
	ds_read_b128 v[48:51], v121 offset:25792
	s_waitcnt lgkmcnt(1)
	v_mfma_f32_16x16x32_bf16 v[12:15], v[52:55], v[16:19], v[12:15]
	s_waitcnt lgkmcnt(0)
	v_mfma_f32_16x16x32_bf16 v[12:15], v[48:51], v[20:23], v[12:15]
	v_add_co_u32_e32 v48, vcc, s28, v80
	s_nop 1
	v_addc_co_u32_e32 v49, vcc, 0, v81, vcc
	v_add_co_u32_e32 v52, vcc, s28, v118
	s_barrier
; #define MFMA(a, b, c) __builtin_amdgcn_mfma_f32_16x16x32_bf16((a), (b), (c), 0, 0, 0)
; DI void mem_attn_prompt_block(const Params& p, int item, char* smem) {
;     ...
;   for (int c = 0; c < 4; ++c) {
;     __syncthreads();
; #pragma unroll
;     for (int i2 = 0; i2 < 2; ++i2) {
; #pragma unroll
;       for (int i = i2 * 4; i < i2 * 4 + 4; ++i) {
;         const int idx = tid + 256 * i, row = idx >> 5, seg = idx & 31;
;         *(bf16x8*)&sK[row * 264 + seg * 8] = *(gb8p)((gu16p)kbp + (size_t)(c * 64 + row) * 256 + seg * 8);
;       }
;       __builtin_amdgcn_sched_barrier(0);
;     }
;     __syncthreads();
; #pragma unroll
;     for (int m4 = 0; m4 < 4; ++m4) {
;       f32x4 a = (f32x4){0.f, 0.f, 0.f, 0.f};
; #pragma unroll
;       for (int ks = 0; ks < 8; ++ks) {
;         bf16x8 kf = *(const bf16x8*)&sK[(m4 * 16 + r) * 264 + ks * 32 + kg * 8];
;         a = MFMA(kf, qf[ks], a);
;       }
;       st[c * 4 + m4] = a;
;       __builtin_amdgcn_sched_barrier(0);
;     }
;   }
	s_nop 0
	v_addc_co_u32_e32 v53, vcc, 0, v119, vcc
	v_add_co_u32_e32 v56, vcc, s28, v90
	s_nop 1
	v_addc_co_u32_e32 v57, vcc, 0, v91, vcc
	v_add_co_u32_e32 v60, vcc, s28, v86
	global_load_dwordx4 v[48:51], v[48:49], off
	s_nop 0
	global_load_dwordx4 v[52:55], v[52:53], off
	v_addc_co_u32_e32 v61, vcc, 0, v87, vcc
	global_load_dwordx4 v[56:59], v[56:57], off
	s_nop 0
	global_load_dwordx4 v[60:63], v[60:61], off
	v_add_co_u32_e32 v204, vcc, s29, v80
	s_nop 1
	v_addc_co_u32_e32 v205, vcc, 0, v81, vcc
	v_add_co_u32_e32 v208, vcc, s28, v88
	s_nop 1
	v_addc_co_u32_e32 v209, vcc, 0, v89, vcc
	v_add_co_u32_e32 v212, vcc, s28, v84
	global_load_dwordx4 v[204:207], v[204:205], off
	s_nop 0
	global_load_dwordx4 v[208:211], v[208:209], off
	v_addc_co_u32_e32 v213, vcc, 0, v85, vcc
	v_add_co_u32_e32 v216, vcc, s28, v82
	s_nop 1
	v_addc_co_u32_e32 v217, vcc, 0, v83, vcc
	global_load_dwordx4 v[212:215], v[212:213], off
	s_nop 0
	global_load_dwordx4 v[216:219], v[216:217], off
	s_waitcnt vmcnt(7)
	ds_write_b128 v130, v[48:51]
	s_waitcnt vmcnt(6)
	ds_write_b128 v131, v[52:55]
	s_waitcnt vmcnt(5)
	ds_write_b128 v137, v[56:59]
	s_waitcnt vmcnt(4)
	ds_write_b128 v142, v[60:63]
	s_waitcnt vmcnt(3)
	ds_write_b128 v130, v[204:207] offset:16896
	s_waitcnt vmcnt(2)
	ds_write_b128 v145, v[208:211]
	s_waitcnt vmcnt(1)
	ds_write_b128 v146, v[212:215]
	s_waitcnt vmcnt(0)
	ds_write_b128 v147, v[216:219]
	s_waitcnt lgkmcnt(0)
	s_barrier
	ds_read_b128 v[48:51], v121
	ds_read_b128 v[52:55], v121 offset:64
	s_waitcnt lgkmcnt(1)
	v_mfma_f32_16x16x32_bf16 v[48:51], v[48:51], v[44:47], 0
	ds_read_b128 v[56:59], v121 offset:128
	s_waitcnt lgkmcnt(1)
	v_mfma_f32_16x16x32_bf16 v[48:51], v[52:55], v[40:43], v[48:51]
	ds_read_b128 v[52:55], v121 offset:192
	s_waitcnt lgkmcnt(1)
	v_mfma_f32_16x16x32_bf16 v[48:51], v[56:59], v[36:39], v[48:51]
	ds_read_b128 v[56:59], v121 offset:256
	s_waitcnt lgkmcnt(1)
	v_mfma_f32_16x16x32_bf16 v[48:51], v[52:55], v[32:35], v[48:51]
	ds_read_b128 v[52:55], v121 offset:320
	s_waitcnt lgkmcnt(1)
	v_mfma_f32_16x16x32_bf16 v[48:51], v[56:59], v[28:31], v[48:51]
	ds_read_b128 v[56:59], v121 offset:384
	s_waitcnt lgkmcnt(1)
	v_mfma_f32_16x16x32_bf16 v[48:51], v[52:55], v[24:27], v[48:51]
	ds_read_b128 v[52:55], v121 offset:448
	s_waitcnt lgkmcnt(1)
	v_mfma_f32_16x16x32_bf16 v[48:51], v[56:59], v[16:19], v[48:51]
	s_waitcnt lgkmcnt(0)
	v_mfma_f32_16x16x32_bf16 v[48:51], v[52:55], v[20:23], v[48:51]
	ds_read_b128 v[52:55], v121 offset:8448
	ds_read_b128 v[56:59], v121 offset:8512
	ds_read_b128 v[60:63], v121 offset:8576
	s_waitcnt lgkmcnt(2)
	v_mfma_f32_16x16x32_bf16 v[52:55], v[52:55], v[44:47], 0
	s_waitcnt lgkmcnt(1)
	v_mfma_f32_16x16x32_bf16 v[52:55], v[56:59], v[40:43], v[52:55]
	ds_read_b128 v[56:59], v121 offset:8640
	s_waitcnt lgkmcnt(1)
	v_mfma_f32_16x16x32_bf16 v[52:55], v[60:63], v[36:39], v[52:55]
	ds_read_b128 v[60:63], v121 offset:8704
	s_waitcnt lgkmcnt(1)
	v_mfma_f32_16x16x32_bf16 v[52:55], v[56:59], v[32:35], v[52:55]
	ds_read_b128 v[56:59], v121 offset:8768
	s_waitcnt lgkmcnt(1)
	v_mfma_f32_16x16x32_bf16 v[52:55], v[60:63], v[28:31], v[52:55]
	ds_read_b128 v[60:63], v121 offset:8832
	s_waitcnt lgkmcnt(1)
	v_mfma_f32_16x16x32_bf16 v[52:55], v[56:59], v[24:27], v[52:55]
	ds_read_b128 v[56:59], v121 offset:8896
	s_waitcnt lgkmcnt(1)
	v_mfma_f32_16x16x32_bf16 v[52:55], v[60:63], v[16:19], v[52:55]
	s_waitcnt lgkmcnt(0)
	v_mfma_f32_16x16x32_bf16 v[52:55], v[56:59], v[20:23], v[52:55]
	ds_read_b128 v[56:59], v121 offset:16896
	ds_read_b128 v[60:63], v121 offset:16960
	ds_read_b128 v[64:67], v121 offset:17024
	s_waitcnt lgkmcnt(2)
	v_mfma_f32_16x16x32_bf16 v[56:59], v[56:59], v[44:47], 0
	s_waitcnt lgkmcnt(1)
	v_mfma_f32_16x16x32_bf16 v[56:59], v[60:63], v[40:43], v[56:59]
	ds_read_b128 v[60:63], v121 offset:17088
	s_waitcnt lgkmcnt(1)
	v_mfma_f32_16x16x32_bf16 v[56:59], v[64:67], v[36:39], v[56:59]
	ds_read_b128 v[64:67], v121 offset:17152
	s_waitcnt lgkmcnt(1)
	v_mfma_f32_16x16x32_bf16 v[56:59], v[60:63], v[32:35], v[56:59]
	ds_read_b128 v[60:63], v121 offset:17216
	s_waitcnt lgkmcnt(1)
	v_mfma_f32_16x16x32_bf16 v[56:59], v[64:67], v[28:31], v[56:59]
	ds_read_b128 v[64:67], v121 offset:17280
	s_waitcnt lgkmcnt(1)
	v_mfma_f32_16x16x32_bf16 v[56:59], v[60:63], v[24:27], v[56:59]
	ds_read_b128 v[60:63], v121 offset:17344
	s_waitcnt lgkmcnt(1)
	v_mfma_f32_16x16x32_bf16 v[56:59], v[64:67], v[16:19], v[56:59]
	s_waitcnt lgkmcnt(0)
	v_mfma_f32_16x16x32_bf16 v[56:59], v[60:63], v[20:23], v[56:59]
	ds_read_b128 v[60:63], v121 offset:25344
	ds_read_b128 v[64:67], v121 offset:25408
	ds_read_b128 v[68:71], v121 offset:25472
	s_waitcnt lgkmcnt(2)
	v_mfma_f32_16x16x32_bf16 v[60:63], v[60:63], v[44:47], 0
	s_waitcnt lgkmcnt(1)
	v_mfma_f32_16x16x32_bf16 v[60:63], v[64:67], v[40:43], v[60:63]
	ds_read_b128 v[64:67], v121 offset:25536
	s_waitcnt lgkmcnt(1)
	v_mfma_f32_16x16x32_bf16 v[60:63], v[68:71], v[36:39], v[60:63]
	ds_read_b128 v[68:71], v121 offset:25600
	s_waitcnt lgkmcnt(1)
	v_mfma_f32_16x16x32_bf16 v[60:63], v[64:67], v[32:35], v[60:63]
	ds_read_b128 v[64:67], v121 offset:25664
	s_waitcnt lgkmcnt(1)
	v_mfma_f32_16x16x32_bf16 v[60:63], v[68:71], v[28:31], v[60:63]
	ds_read_b128 v[68:71], v121 offset:25728
	s_waitcnt lgkmcnt(1)
	v_mfma_f32_16x16x32_bf16 v[60:63], v[64:67], v[24:27], v[60:63]
	ds_read_b128 v[64:67], v121 offset:25792
	s_waitcnt lgkmcnt(1)
	v_mfma_f32_16x16x32_bf16 v[60:63], v[68:71], v[16:19], v[60:63]
	s_waitcnt lgkmcnt(0)
	v_mfma_f32_16x16x32_bf16 v[60:63], v[64:67], v[20:23], v[60:63]
	v_add_co_u32_e32 v64, vcc, s30, v80
	s_nop 1
	v_addc_co_u32_e32 v65, vcc, 0, v81, vcc
	v_add_co_u32_e32 v68, vcc, s30, v118
	s_barrier
; #define MFMA(a, b, c) __builtin_amdgcn_mfma_f32_16x16x32_bf16((a), (b), (c), 0, 0, 0)
; DI void mem_attn_prompt_block(const Params& p, int item, char* smem) {
;     ...
;   for (int c = 0; c < 4; ++c) {
;     __syncthreads();
; #pragma unroll
;     for (int i2 = 0; i2 < 2; ++i2) {
; #pragma unroll
;       for (int i = i2 * 4; i < i2 * 4 + 4; ++i) {
;         const int idx = tid + 256 * i, row = idx >> 5, seg = idx & 31;
;         *(bf16x8*)&sK[row * 264 + seg * 8] = *(gb8p)((gu16p)kbp + (size_t)(c * 64 + row) * 256 + seg * 8);
;       }
;       __builtin_amdgcn_sched_barrier(0);
;     }
;     __syncthreads();
; #pragma unroll
;     for (int m4 = 0; m4 < 4; ++m4) {
;       f32x4 a = (f32x4){0.f, 0.f, 0.f, 0.f};
; #pragma unroll
;       for (int ks = 0; ks < 8; ++ks) {
;         bf16x8 kf = *(const bf16x8*)&sK[(m4 * 16 + r) * 264 + ks * 32 + kg * 8];
;         a = MFMA(kf, qf[ks], a);
;       }
;       st[c * 4 + m4] = a;
;       __builtin_amdgcn_sched_barrier(0);
;     }
;   }
	s_nop 0
	v_addc_co_u32_e32 v69, vcc, 0, v119, vcc
	v_add_co_u32_e32 v72, vcc, s30, v90
	s_nop 1
	v_addc_co_u32_e32 v73, vcc, 0, v91, vcc
	v_add_co_u32_e32 v76, vcc, s30, v86
	global_load_dwordx4 v[64:67], v[64:65], off
	s_nop 0
	global_load_dwordx4 v[68:71], v[68:69], off
	v_addc_co_u32_e32 v77, vcc, 0, v87, vcc
	global_load_dwordx4 v[72:75], v[72:73], off
	s_nop 0
	global_load_dwordx4 v[76:79], v[76:77], off
	v_add_co_u32_e32 v204, vcc, s31, v80
	s_nop 1
	v_addc_co_u32_e32 v205, vcc, 0, v81, vcc
	v_add_co_u32_e32 v208, vcc, s30, v88
	s_nop 1
	v_addc_co_u32_e32 v209, vcc, 0, v89, vcc
	v_add_co_u32_e32 v212, vcc, s30, v84
	global_load_dwordx4 v[204:207], v[204:205], off
	s_nop 0
	global_load_dwordx4 v[208:211], v[208:209], off
	v_addc_co_u32_e32 v213, vcc, 0, v85, vcc
	v_add_co_u32_e32 v216, vcc, s30, v82
	s_nop 1
	v_addc_co_u32_e32 v217, vcc, 0, v83, vcc
	global_load_dwordx4 v[212:215], v[212:213], off
	s_nop 0
	global_load_dwordx4 v[216:219], v[216:217], off
	s_waitcnt vmcnt(7)
	ds_write_b128 v130, v[64:67]
	s_waitcnt vmcnt(6)
	ds_write_b128 v131, v[68:71]
	s_waitcnt vmcnt(5)
	ds_write_b128 v137, v[72:75]
	s_waitcnt vmcnt(4)
	ds_write_b128 v142, v[76:79]
	s_waitcnt vmcnt(3)
	ds_write_b128 v130, v[204:207] offset:16896
	s_waitcnt vmcnt(2)
	ds_write_b128 v145, v[208:211]
	s_waitcnt vmcnt(1)
	ds_write_b128 v146, v[212:215]
	s_waitcnt vmcnt(0)
	ds_write_b128 v147, v[216:219]
	s_waitcnt lgkmcnt(0)
	s_barrier
	ds_read_b128 v[64:67], v121
	ds_read_b128 v[68:71], v121 offset:64
	s_waitcnt lgkmcnt(1)
	v_mfma_f32_16x16x32_bf16 v[64:67], v[64:67], v[44:47], 0
	ds_read_b128 v[72:75], v121 offset:128
	s_waitcnt lgkmcnt(1)
	v_mfma_f32_16x16x32_bf16 v[64:67], v[68:71], v[40:43], v[64:67]
	ds_read_b128 v[68:71], v121 offset:192
	s_waitcnt lgkmcnt(1)
	v_mfma_f32_16x16x32_bf16 v[64:67], v[72:75], v[36:39], v[64:67]
	ds_read_b128 v[72:75], v121 offset:256
	s_waitcnt lgkmcnt(1)
	v_mfma_f32_16x16x32_bf16 v[64:67], v[68:71], v[32:35], v[64:67]
	ds_read_b128 v[68:71], v121 offset:320
	s_waitcnt lgkmcnt(1)
	v_mfma_f32_16x16x32_bf16 v[64:67], v[72:75], v[28:31], v[64:67]
	ds_read_b128 v[72:75], v121 offset:384
	s_waitcnt lgkmcnt(1)
	v_mfma_f32_16x16x32_bf16 v[64:67], v[68:71], v[24:27], v[64:67]
	ds_read_b128 v[68:71], v121 offset:448
	s_waitcnt lgkmcnt(1)
	v_mfma_f32_16x16x32_bf16 v[64:67], v[72:75], v[16:19], v[64:67]
	s_waitcnt lgkmcnt(0)
	v_mfma_f32_16x16x32_bf16 v[64:67], v[68:71], v[20:23], v[64:67]
	ds_read_b128 v[68:71], v121 offset:8448
	ds_read_b128 v[72:75], v121 offset:8512
	ds_read_b128 v[76:79], v121 offset:8576
	s_waitcnt lgkmcnt(2)
	v_mfma_f32_16x16x32_bf16 v[68:71], v[68:71], v[44:47], 0
	s_waitcnt lgkmcnt(1)
	v_mfma_f32_16x16x32_bf16 v[68:71], v[72:75], v[40:43], v[68:71]
	ds_read_b128 v[72:75], v121 offset:8640
	s_waitcnt lgkmcnt(1)
	v_mfma_f32_16x16x32_bf16 v[68:71], v[76:79], v[36:39], v[68:71]
	ds_read_b128 v[76:79], v121 offset:8704
	s_waitcnt lgkmcnt(1)
	v_mfma_f32_16x16x32_bf16 v[68:71], v[72:75], v[32:35], v[68:71]
	ds_read_b128 v[72:75], v121 offset:8768
	s_waitcnt lgkmcnt(1)
	v_mfma_f32_16x16x32_bf16 v[68:71], v[76:79], v[28:31], v[68:71]
	ds_read_b128 v[76:79], v121 offset:8832
	s_waitcnt lgkmcnt(1)
	v_mfma_f32_16x16x32_bf16 v[68:71], v[72:75], v[24:27], v[68:71]
	ds_read_b128 v[72:75], v121 offset:8896
	s_waitcnt lgkmcnt(1)
	v_mfma_f32_16x16x32_bf16 v[68:71], v[76:79], v[16:19], v[68:71]
	s_waitcnt lgkmcnt(0)
	v_mfma_f32_16x16x32_bf16 v[68:71], v[72:75], v[20:23], v[68:71]
	ds_read_b128 v[72:75], v121 offset:16896
	ds_read_b128 v[76:79], v121 offset:16960
	ds_read_b128 v[156:159], v121 offset:17024
	s_waitcnt lgkmcnt(2)
	v_mfma_f32_16x16x32_bf16 v[72:75], v[72:75], v[44:47], 0
	s_waitcnt lgkmcnt(1)
	v_mfma_f32_16x16x32_bf16 v[72:75], v[76:79], v[40:43], v[72:75]
	ds_read_b128 v[76:79], v121 offset:17088
	s_waitcnt lgkmcnt(1)
	v_mfma_f32_16x16x32_bf16 v[72:75], v[156:159], v[36:39], v[72:75]
	ds_read_b128 v[156:159], v121 offset:17152
	s_waitcnt lgkmcnt(1)
	v_mfma_f32_16x16x32_bf16 v[72:75], v[76:79], v[32:35], v[72:75]
	ds_read_b128 v[76:79], v121 offset:17216
	s_waitcnt lgkmcnt(1)
	v_mfma_f32_16x16x32_bf16 v[72:75], v[156:159], v[28:31], v[72:75]
	ds_read_b128 v[156:159], v121 offset:17280
	s_waitcnt lgkmcnt(1)
	v_mfma_f32_16x16x32_bf16 v[72:75], v[76:79], v[24:27], v[72:75]
	ds_read_b128 v[76:79], v121 offset:17344
	s_waitcnt lgkmcnt(1)
	v_mfma_f32_16x16x32_bf16 v[72:75], v[156:159], v[16:19], v[72:75]
	s_waitcnt lgkmcnt(0)
	v_mfma_f32_16x16x32_bf16 v[72:75], v[76:79], v[20:23], v[72:75]
	ds_read_b128 v[76:79], v121 offset:25344
	ds_read_b128 v[156:159], v121 offset:25408
	ds_read_b128 v[166:169], v121 offset:25472
	s_waitcnt lgkmcnt(2)
	v_mfma_f32_16x16x32_bf16 v[76:79], v[76:79], v[44:47], 0
	s_waitcnt lgkmcnt(1)
	v_mfma_f32_16x16x32_bf16 v[76:79], v[156:159], v[40:43], v[76:79]
	ds_read_b128 v[156:159], v121 offset:25536
	s_waitcnt lgkmcnt(1)
	v_mfma_f32_16x16x32_bf16 v[76:79], v[166:169], v[36:39], v[76:79]
	ds_read_b128 v[166:169], v121 offset:25600
	s_waitcnt lgkmcnt(1)
	v_mfma_f32_16x16x32_bf16 v[76:79], v[156:159], v[32:35], v[76:79]
	ds_read_b128 v[156:159], v121 offset:25664
	s_waitcnt lgkmcnt(1)
	v_mfma_f32_16x16x32_bf16 v[76:79], v[166:169], v[28:31], v[76:79]
	ds_read_b128 v[166:169], v121 offset:25728
	s_waitcnt lgkmcnt(1)
	v_mfma_f32_16x16x32_bf16 v[76:79], v[156:159], v[24:27], v[76:79]
	ds_read_b128 v[156:159], v121 offset:25792
	s_waitcnt lgkmcnt(1)
	v_mfma_f32_16x16x32_bf16 v[76:79], v[166:169], v[16:19], v[76:79]
	s_waitcnt lgkmcnt(0)
	v_mfma_f32_16x16x32_bf16 v[76:79], v[156:159], v[20:23], v[76:79]
	v_add_co_u32_e32 v156, vcc, s34, v80
	s_nop 1
	v_addc_co_u32_e32 v157, vcc, 0, v81, vcc
	v_add_co_u32_e32 v118, vcc, s34, v118
	s_barrier
; #define MFMA(a, b, c) __builtin_amdgcn_mfma_f32_16x16x32_bf16((a), (b), (c), 0, 0, 0)
; DI void mem_attn_prompt_block(const Params& p, int item, char* smem) {
;     ...
;   for (int c = 0; c < 4; ++c) {
;     __syncthreads();
; #pragma unroll
;     for (int i2 = 0; i2 < 2; ++i2) {
; #pragma unroll
;       for (int i = i2 * 4; i < i2 * 4 + 4; ++i) {
;         const int idx = tid + 256 * i, row = idx >> 5, seg = idx & 31;
;         *(bf16x8*)&sK[row * 264 + seg * 8] = *(gb8p)((gu16p)kbp + (size_t)(c * 64 + row) * 256 + seg * 8);
;       }
;       __builtin_amdgcn_sched_barrier(0);
;     }
;     __syncthreads();
; #pragma unroll
;     for (int m4 = 0; m4 < 4; ++m4) {
;       f32x4 a = (f32x4){0.f, 0.f, 0.f, 0.f};
; #pragma unroll
;       for (int ks = 0; ks < 8; ++ks) {
;         bf16x8 kf = *(const bf16x8*)&sK[(m4 * 16 + r) * 264 + ks * 32 + kg * 8];
;         a = MFMA(kf, qf[ks], a);
;       }
;       st[c * 4 + m4] = a;
;       __builtin_amdgcn_sched_barrier(0);
;     }
	s_nop 0
	v_addc_co_u32_e32 v119, vcc, 0, v119, vcc
	v_add_co_u32_e32 v90, vcc, s34, v90
	s_nop 1
	v_addc_co_u32_e32 v91, vcc, 0, v91, vcc
	v_add_co_u32_e32 v86, vcc, s34, v86
	global_load_dwordx4 v[156:159], v[156:157], off
	s_nop 0
	global_load_dwordx4 v[166:169], v[118:119], off
	v_addc_co_u32_e32 v87, vcc, 0, v87, vcc
	global_load_dwordx4 v[192:195], v[90:91], off
	global_load_dwordx4 v[198:201], v[86:87], off
	v_add_co_u32_e32 v212, vcc, s35, v80
	s_nop 1
	v_addc_co_u32_e32 v213, vcc, 0, v81, vcc
	v_add_co_u32_e32 v90, vcc, s34, v88
	s_nop 1
	v_addc_co_u32_e32 v91, vcc, 0, v89, vcc
	global_load_dwordx4 v[204:207], v[212:213], off
	global_load_dwordx4 v[208:211], v[90:91], off
	v_add_co_u32_e32 v212, vcc, s34, v84
	s_nop 1
	v_addc_co_u32_e32 v213, vcc, 0, v85, vcc
	v_add_co_u32_e32 v84, vcc, s34, v82
	s_nop 1
	v_addc_co_u32_e32 v85, vcc, 0, v83, vcc
	global_load_dwordx4 v[212:215], v[212:213], off
	s_nop 0
	global_load_dwordx4 v[216:219], v[84:85], off
	s_waitcnt vmcnt(7)
	ds_write_b128 v130, v[156:159]
	s_waitcnt vmcnt(6)
	ds_write_b128 v131, v[166:169]
	s_waitcnt vmcnt(5)
	ds_write_b128 v137, v[192:195]
	s_waitcnt vmcnt(4)
	ds_write_b128 v142, v[198:201]
	s_waitcnt vmcnt(3)
	ds_write_b128 v130, v[204:207] offset:16896
	s_waitcnt vmcnt(2)
	ds_write_b128 v145, v[208:211]
	s_waitcnt vmcnt(1)
	ds_write_b128 v146, v[212:215]
	s_waitcnt vmcnt(0)
	ds_write_b128 v147, v[216:219]
	s_waitcnt lgkmcnt(0)
	s_barrier
	ds_read_b128 v[80:83], v121
	ds_read_b128 v[84:87], v121 offset:64
	s_waitcnt lgkmcnt(1)
	v_mfma_f32_16x16x32_bf16 v[80:83], v[80:83], v[44:47], 0
	ds_read_b128 v[88:91], v121 offset:128
	s_waitcnt lgkmcnt(1)
	v_mfma_f32_16x16x32_bf16 v[80:83], v[84:87], v[40:43], v[80:83]
	ds_read_b128 v[84:87], v121 offset:192
	s_waitcnt lgkmcnt(1)
	v_mfma_f32_16x16x32_bf16 v[80:83], v[88:91], v[36:39], v[80:83]
	ds_read_b128 v[88:91], v121 offset:256
	s_waitcnt lgkmcnt(1)
	v_mfma_f32_16x16x32_bf16 v[80:83], v[84:87], v[32:35], v[80:83]
	ds_read_b128 v[84:87], v121 offset:320
	s_waitcnt lgkmcnt(1)
	v_mfma_f32_16x16x32_bf16 v[80:83], v[88:91], v[28:31], v[80:83]
	ds_read_b128 v[88:91], v121 offset:384
	s_waitcnt lgkmcnt(1)
	v_mfma_f32_16x16x32_bf16 v[80:83], v[84:87], v[24:27], v[80:83]
	ds_read_b128 v[84:87], v121 offset:448
	s_waitcnt lgkmcnt(1)
	v_mfma_f32_16x16x32_bf16 v[80:83], v[88:91], v[16:19], v[80:83]
	s_waitcnt lgkmcnt(0)
	v_mfma_f32_16x16x32_bf16 v[80:83], v[84:87], v[20:23], v[80:83]
	ds_read_b128 v[84:87], v121 offset:8448
	ds_read_b128 v[88:91], v121 offset:8512
	ds_read_b128 v[156:159], v121 offset:8576
	s_waitcnt lgkmcnt(2)
	v_mfma_f32_16x16x32_bf16 v[84:87], v[84:87], v[44:47], 0
	s_waitcnt lgkmcnt(1)
	v_mfma_f32_16x16x32_bf16 v[84:87], v[88:91], v[40:43], v[84:87]
	ds_read_b128 v[88:91], v121 offset:8640
	s_waitcnt lgkmcnt(1)
	v_mfma_f32_16x16x32_bf16 v[84:87], v[156:159], v[36:39], v[84:87]
	ds_read_b128 v[156:159], v121 offset:8704
	s_waitcnt lgkmcnt(1)
	v_mfma_f32_16x16x32_bf16 v[84:87], v[88:91], v[32:35], v[84:87]
	ds_read_b128 v[88:91], v121 offset:8768
	s_waitcnt lgkmcnt(1)
	v_mfma_f32_16x16x32_bf16 v[84:87], v[156:159], v[28:31], v[84:87]
	ds_read_b128 v[156:159], v121 offset:8832
	s_waitcnt lgkmcnt(1)
	v_mfma_f32_16x16x32_bf16 v[84:87], v[88:91], v[24:27], v[84:87]
	ds_read_b128 v[88:91], v121 offset:8896
	s_waitcnt lgkmcnt(1)
	v_mfma_f32_16x16x32_bf16 v[84:87], v[156:159], v[16:19], v[84:87]
	s_waitcnt lgkmcnt(0)
	v_mfma_f32_16x16x32_bf16 v[84:87], v[88:91], v[20:23], v[84:87]
	ds_read_b128 v[88:91], v121 offset:16896
	ds_read_b128 v[156:159], v121 offset:16960
	ds_read_b128 v[166:169], v121 offset:17024
	s_waitcnt lgkmcnt(2)
	v_mfma_f32_16x16x32_bf16 v[88:91], v[88:91], v[44:47], 0
	s_waitcnt lgkmcnt(1)
	v_mfma_f32_16x16x32_bf16 v[88:91], v[156:159], v[40:43], v[88:91]
	ds_read_b128 v[156:159], v121 offset:17088
	s_waitcnt lgkmcnt(1)
	v_mfma_f32_16x16x32_bf16 v[88:91], v[166:169], v[36:39], v[88:91]
	ds_read_b128 v[166:169], v121 offset:17152
	s_waitcnt lgkmcnt(1)
	v_mfma_f32_16x16x32_bf16 v[88:91], v[156:159], v[32:35], v[88:91]
	ds_read_b128 v[156:159], v121 offset:17216
	s_waitcnt lgkmcnt(1)
	v_mfma_f32_16x16x32_bf16 v[88:91], v[166:169], v[28:31], v[88:91]
	ds_read_b128 v[166:169], v121 offset:17280
	s_waitcnt lgkmcnt(1)
	v_mfma_f32_16x16x32_bf16 v[88:91], v[156:159], v[24:27], v[88:91]
	ds_read_b128 v[156:159], v121 offset:17344
	s_waitcnt lgkmcnt(1)
	v_mfma_f32_16x16x32_bf16 v[88:91], v[166:169], v[16:19], v[88:91]
	s_waitcnt lgkmcnt(0)
	v_mfma_f32_16x16x32_bf16 v[88:91], v[156:159], v[20:23], v[88:91]
	ds_read_b128 v[156:159], v121 offset:25344
	ds_read_b128 v[166:169], v121 offset:25408
	s_waitcnt lgkmcnt(1)
	v_mfma_f32_16x16x32_bf16 v[44:47], v[156:159], v[44:47], 0
	ds_read_b128 v[156:159], v121 offset:25472
	s_waitcnt lgkmcnt(1)
	v_mfma_f32_16x16x32_bf16 v[40:43], v[166:169], v[40:43], v[44:47]
	s_nop 4
	ds_read_b128 v[44:47], v121 offset:25536
	s_waitcnt lgkmcnt(1)
	v_mfma_f32_16x16x32_bf16 v[36:39], v[156:159], v[36:39], v[40:43]
	s_nop 2
	ds_read_b128 v[40:43], v121 offset:25600
	s_waitcnt lgkmcnt(1)
	v_mfma_f32_16x16x32_bf16 v[32:35], v[44:47], v[32:35], v[36:39]
	s_nop 2
	ds_read_b128 v[36:39], v121 offset:25664
	s_waitcnt lgkmcnt(1)
	v_mfma_f32_16x16x32_bf16 v[28:31], v[40:43], v[28:31], v[32:35]
	s_nop 2
	ds_read_b128 v[32:35], v121 offset:25728
	s_waitcnt lgkmcnt(1)
	v_mfma_f32_16x16x32_bf16 v[24:27], v[36:39], v[24:27], v[28:31]
	s_nop 2
	ds_read_b128 v[28:31], v121 offset:25792
	s_waitcnt lgkmcnt(1)
	v_mfma_f32_16x16x32_bf16 v[16:19], v[32:35], v[16:19], v[24:27]
	s_waitcnt lgkmcnt(0)
; #define MFMA(a, b, c) __builtin_amdgcn_mfma_f32_16x16x32_bf16((a), (b), (c), 0, 0, 0)
; DI void mem_attn_prompt_block(const Params& p, int item, char* smem) {
;     ...
;       for (int ks = 0; ks < 8; ++ks) {
;         bf16x8 kf = *(const bf16x8*)&sK[(m4 * 16 + r) * 264 + ks * 32 + kg * 8];
;         a = MFMA(kf, qf[ks], a);
;       }
;       st[c * 4 + m4] = a;
;       __builtin_amdgcn_sched_barrier(0);
;     }
;   }
;   float mx = -3.0e38f;
; #pragma unroll
;   for (int mt = 0; mt < 16; ++mt)
; #pragma unroll
;     for (int j = 0; j < 4; ++j) { st[mt][j] *= 0.0625f; mx = fmaxf(mx, st[mt][j]); }
;   mx = fmaxf(mx, __shfl_xor(mx, 16));
;   mx = fmaxf(mx, __shfl_xor(mx, 32));
;   float sum = 0.f;
; #pragma unroll
;   for (int mt = 0; mt < 16; ++mt)
; #pragma unroll
;     for (int j = 0; j < 4; ++j) { st[mt][j] = __expf(st[mt][j] - mx); sum += st[mt][j]; }
	v_mfma_f32_16x16x32_bf16 v[16:19], v[28:31], v[20:23], v[16:19]
	v_mul_f32_e32 v20, 0x3d800000, v0
	v_mul_f32_e32 v21, 0x3d800000, v1
	v_max3_f32 v20, v20, s37, v21
	v_mul_f32_e32 v21, 0x3d800000, v2
	v_mul_f32_e32 v22, 0x3d800000, v3
	v_max3_f32 v20, v20, v21, v22
	v_mul_f32_e32 v21, 0x3d800000, v4
	v_mul_f32_e32 v22, 0x3d800000, v5
	v_max3_f32 v20, v20, v21, v22
	v_mul_f32_e32 v21, 0x3d800000, v6
	v_mul_f32_e32 v22, 0x3d800000, v7
	v_max3_f32 v20, v20, v21, v22
	v_mul_f32_e32 v21, 0x3d800000, v8
	v_mul_f32_e32 v22, 0x3d800000, v9
	v_max3_f32 v20, v20, v21, v22
	v_mul_f32_e32 v21, 0x3d800000, v10
	v_mul_f32_e32 v22, 0x3d800000, v11
	v_max3_f32 v20, v20, v21, v22
	v_mul_f32_e32 v21, 0x3d800000, v12
	v_mul_f32_e32 v22, 0x3d800000, v13
	v_max3_f32 v20, v20, v21, v22
	v_mul_f32_e32 v21, 0x3d800000, v14
	v_mul_f32_e32 v22, 0x3d800000, v15
	v_max3_f32 v20, v20, v21, v22
	v_mul_f32_e32 v21, 0x3d800000, v48
	v_mul_f32_e32 v22, 0x3d800000, v49
	v_max3_f32 v20, v20, v21, v22
	v_mul_f32_e32 v21, 0x3d800000, v50
	v_mul_f32_e32 v22, 0x3d800000, v51
	v_max3_f32 v20, v20, v21, v22
	v_mul_f32_e32 v21, 0x3d800000, v52
	v_mul_f32_e32 v22, 0x3d800000, v53
	v_max3_f32 v20, v20, v21, v22
	v_mul_f32_e32 v21, 0x3d800000, v54
	v_mul_f32_e32 v22, 0x3d800000, v55
	v_max3_f32 v20, v20, v21, v22
	v_mul_f32_e32 v21, 0x3d800000, v56
	v_mul_f32_e32 v22, 0x3d800000, v57
	v_max3_f32 v20, v20, v21, v22
	v_mul_f32_e32 v21, 0x3d800000, v58
	v_mul_f32_e32 v22, 0x3d800000, v59
	v_max3_f32 v20, v20, v21, v22
	v_mul_f32_e32 v21, 0x3d800000, v60
	v_mul_f32_e32 v22, 0x3d800000, v61
	v_max3_f32 v20, v20, v21, v22
	v_mul_f32_e32 v21, 0x3d800000, v62
	v_mul_f32_e32 v22, 0x3d800000, v63
	v_max3_f32 v20, v20, v21, v22
	v_mul_f32_e32 v21, 0x3d800000, v64
	v_mul_f32_e32 v22, 0x3d800000, v65
	v_max3_f32 v20, v20, v21, v22
	v_mul_f32_e32 v21, 0x3d800000, v66
	v_mul_f32_e32 v22, 0x3d800000, v67
	v_max3_f32 v20, v20, v21, v22
	v_mul_f32_e32 v21, 0x3d800000, v68
	v_mul_f32_e32 v22, 0x3d800000, v69
	v_max3_f32 v20, v20, v21, v22
	v_mul_f32_e32 v21, 0x3d800000, v70
	v_mul_f32_e32 v22, 0x3d800000, v71
	v_max3_f32 v20, v20, v21, v22
	v_mul_f32_e32 v21, 0x3d800000, v72
	v_mul_f32_e32 v22, 0x3d800000, v73
	v_max3_f32 v20, v20, v21, v22
	v_mul_f32_e32 v21, 0x3d800000, v74
	v_mul_f32_e32 v22, 0x3d800000, v75
	v_max3_f32 v20, v20, v21, v22
	v_mul_f32_e32 v21, 0x3d800000, v76
	v_mul_f32_e32 v22, 0x3d800000, v77
	v_max3_f32 v20, v20, v21, v22
	v_mul_f32_e32 v21, 0x3d800000, v78
	v_mul_f32_e32 v22, 0x3d800000, v79
	v_max3_f32 v20, v20, v21, v22
	v_mul_f32_e32 v21, 0x3d800000, v80
	v_mul_f32_e32 v22, 0x3d800000, v81
	v_max3_f32 v20, v20, v21, v22
	v_mul_f32_e32 v21, 0x3d800000, v82
	v_mul_f32_e32 v22, 0x3d800000, v83
	v_max3_f32 v20, v20, v21, v22
	v_mul_f32_e32 v21, 0x3d800000, v84
	v_mul_f32_e32 v22, 0x3d800000, v85
	v_max3_f32 v20, v20, v21, v22
	v_mul_f32_e32 v21, 0x3d800000, v86
	v_mul_f32_e32 v22, 0x3d800000, v87
	v_max3_f32 v20, v20, v21, v22
	v_mul_f32_e32 v21, 0x3d800000, v88
	v_mul_f32_e32 v22, 0x3d800000, v89
	v_max3_f32 v20, v20, v21, v22
	v_mul_f32_e32 v21, 0x3d800000, v90
	v_mul_f32_e32 v22, 0x3d800000, v91
	v_max3_f32 v20, v20, v21, v22
	v_mul_f32_e32 v21, 0x3d800000, v16
	v_mul_f32_e32 v22, 0x3d800000, v17
	v_max3_f32 v20, v20, v21, v22
	v_mul_f32_e32 v21, 0x3d800000, v18
	v_mul_f32_e32 v22, 0x3d800000, v19
	v_cmp_lt_i32_e32 vcc, v152, v153
	v_max3_f32 v20, v20, v21, v22
	s_nop 0
	v_cndmask_b32_e32 v21, v128, v152, vcc
	v_lshlrev_b32_e32 v21, 2, v21
	ds_bpermute_b32 v22, v21, v20
	v_cmp_lt_i32_e32 vcc, v154, v153
	s_waitcnt lgkmcnt(0)
	v_max_f32_e32 v22, v22, v22
	v_max_f32_e32 v20, v20, v22
	v_cndmask_b32_e32 v22, v128, v154, vcc
	v_lshlrev_b32_e32 v22, 2, v22
	ds_bpermute_b32 v23, v22, v20
	s_waitcnt lgkmcnt(0)
	v_max_f32_e32 v23, v23, v23
	v_max_f32_e32 v20, v20, v23
	v_fma_f32 v0, v0, s36, -v20
	v_mul_f32_e32 v0, 0x3fb8aa3b, v0
	v_fma_f32 v1, v1, s36, -v20
	v_exp_f32_e32 v0, v0
	v_mul_f32_e32 v1, 0x3fb8aa3b, v1
	v_fma_f32 v2, v2, s36, -v20
	v_exp_f32_e32 v1, v1
	v_mul_f32_e32 v2, 0x3fb8aa3b, v2
	v_fma_f32 v3, v3, s36, -v20
	v_exp_f32_e32 v2, v2
	v_mul_f32_e32 v3, 0x3fb8aa3b, v3
	v_fma_f32 v4, v4, s36, -v20
	v_exp_f32_e32 v3, v3
	v_mul_f32_e32 v4, 0x3fb8aa3b, v4
	v_fma_f32 v5, v5, s36, -v20
	v_add_f32_e32 v23, 0, v0
	v_exp_f32_e32 v4, v4
	v_mul_f32_e32 v5, 0x3fb8aa3b, v5
	v_fma_f32 v6, v6, s36, -v20
	v_add_f32_e32 v23, v1, v23
	v_exp_f32_e32 v5, v5
	v_mul_f32_e32 v6, 0x3fb8aa3b, v6
	v_fma_f32 v7, v7, s36, -v20
	v_add_f32_e32 v23, v2, v23
	v_exp_f32_e32 v6, v6
	v_mul_f32_e32 v7, 0x3fb8aa3b, v7
	v_fma_f32 v8, v8, s36, -v20
	v_add_f32_e32 v23, v3, v23
	v_exp_f32_e32 v7, v7
	v_mul_f32_e32 v8, 0x3fb8aa3b, v8
	v_fma_f32 v9, v9, s36, -v20
	v_add_f32_e32 v23, v4, v23
	v_exp_f32_e32 v8, v8
	v_mul_f32_e32 v9, 0x3fb8aa3b, v9
	v_fma_f32 v10, v10, s36, -v20
	v_add_f32_e32 v23, v5, v23
	v_exp_f32_e32 v9, v9
	v_mul_f32_e32 v10, 0x3fb8aa3b, v10
	v_fma_f32 v11, v11, s36, -v20
	v_add_f32_e32 v23, v6, v23
	v_exp_f32_e32 v10, v10
	v_mul_f32_e32 v11, 0x3fb8aa3b, v11
	v_fma_f32 v12, v12, s36, -v20
	v_add_f32_e32 v23, v7, v23
	v_exp_f32_e32 v11, v11
	v_mul_f32_e32 v12, 0x3fb8aa3b, v12
	v_fma_f32 v13, v13, s36, -v20
	v_add_f32_e32 v23, v8, v23
	v_exp_f32_e32 v12, v12
	v_mul_f32_e32 v13, 0x3fb8aa3b, v13
	v_fma_f32 v14, v14, s36, -v20
	v_add_f32_e32 v23, v9, v23
	v_exp_f32_e32 v13, v13
	v_mul_f32_e32 v14, 0x3fb8aa3b, v14
	v_fma_f32 v15, v15, s36, -v20
	v_add_f32_e32 v23, v10, v23
	v_exp_f32_e32 v14, v14
	v_mul_f32_e32 v15, 0x3fb8aa3b, v15
	v_fma_f32 v24, v48, s36, -v20
	v_add_f32_e32 v23, v11, v23
	v_exp_f32_e32 v15, v15
	v_mul_f32_e32 v24, 0x3fb8aa3b, v24
	v_fma_f32 v25, v49, s36, -v20
	v_add_f32_e32 v23, v12, v23
; DI void mem_attn_prompt_block(const Params& p, int item, char* smem) {
;     ...
;   float sum = 0.f;
; #pragma unroll
;   for (int mt = 0; mt < 16; ++mt)
; #pragma unroll
;     for (int j = 0; j < 4; ++j) { st[mt][j] = __expf(st[mt][j] - mx); sum += st[mt][j]; }
;   sum += __shfl_xor(sum, 16);
;   sum += __shfl_xor(sum, 32);
;   const float inv = 1.f / sum;
;   bf16x8 pf[8];
; #pragma unroll
;   for (int k2 = 0; k2 < 8; ++k2) pf[k2] = pack8(st[2 * k2], st[2 * k2 + 1]);
	v_exp_f32_e32 v24, v24
	v_mul_f32_e32 v25, 0x3fb8aa3b, v25
	v_fma_f32 v26, v50, s36, -v20
	v_add_f32_e32 v23, v13, v23
	v_exp_f32_e32 v25, v25
	v_mul_f32_e32 v26, 0x3fb8aa3b, v26
	v_fma_f32 v27, v51, s36, -v20
	v_add_f32_e32 v23, v14, v23
	v_exp_f32_e32 v26, v26
	v_mul_f32_e32 v27, 0x3fb8aa3b, v27
	v_fma_f32 v28, v52, s36, -v20
	v_add_f32_e32 v23, v15, v23
	v_exp_f32_e32 v27, v27
	v_mul_f32_e32 v28, 0x3fb8aa3b, v28
	v_fma_f32 v29, v53, s36, -v20
	v_add_f32_e32 v23, v24, v23
	v_exp_f32_e32 v28, v28
	v_mul_f32_e32 v29, 0x3fb8aa3b, v29
	v_fma_f32 v30, v54, s36, -v20
	v_add_f32_e32 v23, v25, v23
	v_exp_f32_e32 v29, v29
	v_mul_f32_e32 v30, 0x3fb8aa3b, v30
	v_fma_f32 v31, v55, s36, -v20
	v_add_f32_e32 v23, v26, v23
	v_exp_f32_e32 v30, v30
	v_mul_f32_e32 v31, 0x3fb8aa3b, v31
	v_fma_f32 v32, v56, s36, -v20
	v_add_f32_e32 v23, v27, v23
	v_exp_f32_e32 v31, v31
	v_mul_f32_e32 v32, 0x3fb8aa3b, v32
	v_fma_f32 v33, v57, s36, -v20
	v_add_f32_e32 v23, v28, v23
	v_exp_f32_e32 v32, v32
	v_mul_f32_e32 v33, 0x3fb8aa3b, v33
	v_fma_f32 v34, v58, s36, -v20
	v_add_f32_e32 v23, v29, v23
	v_exp_f32_e32 v33, v33
	v_mul_f32_e32 v34, 0x3fb8aa3b, v34
	v_fma_f32 v35, v59, s36, -v20
	v_add_f32_e32 v23, v30, v23
	v_exp_f32_e32 v34, v34
	v_mul_f32_e32 v35, 0x3fb8aa3b, v35
	v_fma_f32 v36, v60, s36, -v20
	v_add_f32_e32 v23, v31, v23
	v_exp_f32_e32 v35, v35
	v_mul_f32_e32 v36, 0x3fb8aa3b, v36
	v_fma_f32 v37, v61, s36, -v20
	v_add_f32_e32 v23, v32, v23
	v_exp_f32_e32 v36, v36
	v_mul_f32_e32 v37, 0x3fb8aa3b, v37
	v_fma_f32 v38, v62, s36, -v20
	v_add_f32_e32 v23, v33, v23
	v_exp_f32_e32 v37, v37
	v_mul_f32_e32 v38, 0x3fb8aa3b, v38
	v_fma_f32 v39, v63, s36, -v20
	v_add_f32_e32 v23, v34, v23
	v_exp_f32_e32 v38, v38
	v_mul_f32_e32 v39, 0x3fb8aa3b, v39
	v_fma_f32 v40, v64, s36, -v20
	v_add_f32_e32 v23, v35, v23
	v_exp_f32_e32 v39, v39
	v_mul_f32_e32 v40, 0x3fb8aa3b, v40
	v_fma_f32 v41, v65, s36, -v20
	v_add_f32_e32 v23, v36, v23
	v_exp_f32_e32 v40, v40
	v_mul_f32_e32 v41, 0x3fb8aa3b, v41
	v_fma_f32 v42, v66, s36, -v20
	v_add_f32_e32 v23, v37, v23
	v_exp_f32_e32 v41, v41
	v_mul_f32_e32 v42, 0x3fb8aa3b, v42
	v_fma_f32 v43, v67, s36, -v20
	v_add_f32_e32 v23, v38, v23
	v_exp_f32_e32 v42, v42
	v_mul_f32_e32 v43, 0x3fb8aa3b, v43
	v_fma_f32 v44, v68, s36, -v20
	v_add_f32_e32 v23, v39, v23
	v_exp_f32_e32 v43, v43
	v_mul_f32_e32 v44, 0x3fb8aa3b, v44
	v_fma_f32 v45, v69, s36, -v20
	v_add_f32_e32 v23, v40, v23
	v_exp_f32_e32 v44, v44
	v_mul_f32_e32 v45, 0x3fb8aa3b, v45
	v_fma_f32 v46, v70, s36, -v20
	v_add_f32_e32 v23, v41, v23
	v_exp_f32_e32 v45, v45
	v_mul_f32_e32 v46, 0x3fb8aa3b, v46
	v_fma_f32 v47, v71, s36, -v20
	v_add_f32_e32 v23, v42, v23
	v_exp_f32_e32 v46, v46
	v_mul_f32_e32 v47, 0x3fb8aa3b, v47
	v_fma_f32 v48, v72, s36, -v20
	v_add_f32_e32 v23, v43, v23
	v_exp_f32_e32 v47, v47
	v_mul_f32_e32 v48, 0x3fb8aa3b, v48
	v_fma_f32 v49, v73, s36, -v20
	v_add_f32_e32 v23, v44, v23
	v_exp_f32_e32 v48, v48
	v_mul_f32_e32 v49, 0x3fb8aa3b, v49
	v_fma_f32 v50, v74, s36, -v20
	v_add_f32_e32 v23, v45, v23
	v_exp_f32_e32 v49, v49
	v_mul_f32_e32 v50, 0x3fb8aa3b, v50
	v_fma_f32 v51, v75, s36, -v20
	v_add_f32_e32 v23, v46, v23
	v_exp_f32_e32 v50, v50
	v_mul_f32_e32 v51, 0x3fb8aa3b, v51
	v_fma_f32 v52, v76, s36, -v20
	v_add_f32_e32 v23, v47, v23
	v_exp_f32_e32 v51, v51
	v_mul_f32_e32 v52, 0x3fb8aa3b, v52
	v_fma_f32 v53, v77, s36, -v20
	v_add_f32_e32 v23, v48, v23
	v_exp_f32_e32 v52, v52
	v_mul_f32_e32 v53, 0x3fb8aa3b, v53
	v_fma_f32 v54, v78, s36, -v20
	v_add_f32_e32 v23, v49, v23
	v_exp_f32_e32 v53, v53
	v_mul_f32_e32 v54, 0x3fb8aa3b, v54
	v_fma_f32 v55, v79, s36, -v20
	v_add_f32_e32 v23, v50, v23
	v_exp_f32_e32 v54, v54
	v_mul_f32_e32 v55, 0x3fb8aa3b, v55
	v_fma_f32 v56, v80, s36, -v20
	v_add_f32_e32 v23, v51, v23
	v_exp_f32_e32 v55, v55
	v_mul_f32_e32 v56, 0x3fb8aa3b, v56
	v_fma_f32 v57, v81, s36, -v20
	v_add_f32_e32 v23, v52, v23
	v_exp_f32_e32 v56, v56
	v_mul_f32_e32 v57, 0x3fb8aa3b, v57
	v_fma_f32 v58, v82, s36, -v20
	v_add_f32_e32 v23, v53, v23
	v_exp_f32_e32 v57, v57
	v_mul_f32_e32 v58, 0x3fb8aa3b, v58
	v_fma_f32 v59, v83, s36, -v20
	v_add_f32_e32 v23, v54, v23
	v_exp_f32_e32 v58, v58
	v_mul_f32_e32 v59, 0x3fb8aa3b, v59
	v_fma_f32 v60, v84, s36, -v20
	v_add_f32_e32 v23, v55, v23
	v_exp_f32_e32 v59, v59
	v_mul_f32_e32 v60, 0x3fb8aa3b, v60
	v_fma_f32 v61, v85, s36, -v20
	v_add_f32_e32 v23, v56, v23
	v_exp_f32_e32 v60, v60
	v_mul_f32_e32 v61, 0x3fb8aa3b, v61
	v_fma_f32 v62, v86, s36, -v20
	v_add_f32_e32 v23, v57, v23
	v_exp_f32_e32 v61, v61
	v_mul_f32_e32 v62, 0x3fb8aa3b, v62
	v_fma_f32 v63, v87, s36, -v20
	v_add_f32_e32 v23, v58, v23
	v_exp_f32_e32 v62, v62
	v_mul_f32_e32 v63, 0x3fb8aa3b, v63
	v_fma_f32 v64, v88, s36, -v20
	v_add_f32_e32 v23, v59, v23
	v_exp_f32_e32 v63, v63
	v_mul_f32_e32 v64, 0x3fb8aa3b, v64
	v_fma_f32 v65, v89, s36, -v20
	v_fma_f32 v16, v16, s36, -v20
	v_add_f32_e32 v23, v60, v23
	v_exp_f32_e32 v64, v64
	v_mul_f32_e32 v65, 0x3fb8aa3b, v65
	v_fma_f32 v66, v90, s36, -v20
	v_mul_f32_e32 v16, 0x3fb8aa3b, v16
	v_add_f32_e32 v23, v61, v23
	v_exp_f32_e32 v65, v65
	v_mul_f32_e32 v66, 0x3fb8aa3b, v66
	v_fma_f32 v67, v91, s36, -v20
	v_exp_f32_e32 v68, v16
	v_fma_f32 v16, v17, s36, -v20
	v_add_f32_e32 v23, v62, v23
	v_exp_f32_e32 v66, v66
	v_mul_f32_e32 v67, 0x3fb8aa3b, v67
	v_mul_f32_e32 v16, 0x3fb8aa3b, v16
	v_add_f32_e32 v23, v63, v23
	v_exp_f32_e32 v67, v67
	v_exp_f32_e32 v69, v16
	v_fma_f32 v16, v18, s36, -v20
	v_add_f32_e32 v23, v64, v23
	v_mul_f32_e32 v16, 0x3fb8aa3b, v16
	v_add_f32_e32 v23, v65, v23
	v_exp_f32_e32 v70, v16
	v_fma_f32 v16, v19, s36, -v20
	v_add_f32_e32 v23, v66, v23
	v_mul_f32_e32 v16, 0x3fb8aa3b, v16
	v_add_f32_e32 v23, v67, v23
	v_exp_f32_e32 v71, v16
	v_add_f32_e32 v16, v68, v23
	v_add_f32_e32 v16, v69, v16
	v_add_f32_e32 v16, v70, v16
	v_add_f32_e32 v16, v71, v16
	ds_bpermute_b32 v17, v21, v16
	v_bfe_u32 v18, v3, 16, 1
	v_bfe_u32 v19, v1, 16, 1
	v_add3_u32 v19, v1, v19, s38
	v_add3_u32 v1, v3, v18, s38
	s_waitcnt lgkmcnt(0)
; DI void mem_attn_prompt_block(const Params& p, int item, char* smem) {
;     ...
;   sum += __shfl_xor(sum, 16);
;   sum += __shfl_xor(sum, 32);
;   const float inv = 1.f / sum;
;   bf16x8 pf[8];
; #pragma unroll
;   for (int k2 = 0; k2 < 8; ++k2) pf[k2] = pack8(st[2 * k2], st[2 * k2 + 1]);
;   const u16* vtp = G(p.VTf) + (size_t)bh * 65536;
	v_add_f32_e32 v16, v16, v17
	ds_bpermute_b32 v17, v22, v16
	v_bfe_u32 v18, v6, 16, 1
	v_add3_u32 v6, v6, v18, s38
	v_bfe_u32 v18, v36, 16, 1
	v_add3_u32 v18, v36, v18, s38
	s_waitcnt lgkmcnt(0)
	v_add_f32_e32 v72, v16, v17
	v_bfe_u32 v16, v7, 16, 1
	v_bfe_u32 v17, v5, 16, 1
	v_add3_u32 v5, v5, v17, s38
	v_add3_u32 v3, v7, v16, s38
	v_bfe_u32 v16, v2, 16, 1
	v_bfe_u32 v17, v4, 16, 1
	v_bfe_u32 v7, v0, 16, 1
	v_add3_u32 v4, v4, v17, s38
	v_add3_u32 v2, v2, v16, s38
	v_add3_u32 v0, v0, v7, s38
	v_lshrrev_b32_e32 v7, 16, v2
	v_lshrrev_b32_e32 v2, 16, v4
	v_lshrrev_b32_e32 v4, 16, v6
	v_and_or_b32 v2, v5, s39, v2
	v_and_or_b32 v1, v1, s39, v7
	v_bfe_u32 v5, v13, 16, 1
	v_bfe_u32 v6, v11, 16, 1
	v_bfe_u32 v7, v9, 16, 1
	v_add3_u32 v9, v9, v7, s38
	v_add3_u32 v11, v11, v6, s38
	v_add3_u32 v5, v13, v5, s38
	v_bfe_u32 v6, v8, 16, 1
	v_bfe_u32 v7, v10, 16, 1
	v_bfe_u32 v13, v12, 16, 1
	v_and_or_b32 v3, v3, s39, v4
	v_bfe_u32 v4, v15, 16, 1
	v_add3_u32 v12, v12, v13, s38
	v_add3_u32 v7, v10, v7, s38
	v_add3_u32 v6, v8, v6, s38
	v_add3_u32 v4, v15, v4, s38
	v_bfe_u32 v15, v14, 16, 1
	v_lshrrev_b32_e32 v8, 16, v6
	v_lshrrev_b32_e32 v10, 16, v7
	v_lshrrev_b32_e32 v6, 16, v12
	v_add3_u32 v14, v14, v15, s38
	v_and_or_b32 v6, v5, s39, v6
	v_and_or_b32 v5, v11, s39, v10
	v_bfe_u32 v10, v27, 16, 1
	v_bfe_u32 v11, v25, 16, 1
	v_lshrrev_b32_e32 v7, 16, v14
	v_add3_u32 v12, v25, v11, s38
	v_add3_u32 v13, v27, v10, s38
	v_bfe_u32 v10, v24, 16, 1
	v_bfe_u32 v11, v26, 16, 1
	v_bfe_u32 v14, v28, 16, 1
	v_bfe_u32 v15, v30, 16, 1
	v_and_or_b32 v7, v4, s39, v7
	v_and_or_b32 v4, v9, s39, v8
	v_bfe_u32 v8, v31, 16, 1
	v_bfe_u32 v9, v29, 16, 1
	v_add3_u32 v15, v30, v15, s38
	v_add3_u32 v14, v28, v14, s38
	v_add3_u32 v11, v26, v11, s38
	v_add3_u32 v10, v24, v10, s38
	v_lshrrev_b32_e32 v0, 16, v0
	v_add3_u32 v9, v29, v9, s38
	v_add3_u32 v8, v31, v8, s38
	v_lshrrev_b32_e32 v16, 16, v10
	v_lshrrev_b32_e32 v17, 16, v11
	v_lshrrev_b32_e32 v10, 16, v14
	v_lshrrev_b32_e32 v11, 16, v15
	v_bfe_u32 v14, v35, 16, 1
	v_bfe_u32 v15, v33, 16, 1
	v_and_or_b32 v0, v19, s39, v0
	v_and_or_b32 v11, v8, s39, v11
	v_and_or_b32 v10, v9, s39, v10
	v_and_or_b32 v9, v13, s39, v17
	v_and_or_b32 v8, v12, s39, v16
	v_add3_u32 v16, v33, v15, s38
	v_add3_u32 v17, v35, v14, s38
	v_bfe_u32 v14, v32, 16, 1
	v_bfe_u32 v15, v34, 16, 1
	v_bfe_u32 v19, v38, 16, 1
	v_bfe_u32 v12, v39, 16, 1
	v_bfe_u32 v13, v37, 16, 1
	v_add3_u32 v19, v38, v19, s38
	v_add3_u32 v15, v34, v15, s38
	v_add3_u32 v14, v32, v14, s38
	v_add3_u32 v13, v37, v13, s38
	v_add3_u32 v12, v39, v12, s38
	v_lshrrev_b32_e32 v20, 16, v14
	v_lshrrev_b32_e32 v21, 16, v15
	v_lshrrev_b32_e32 v14, 16, v18
	v_lshrrev_b32_e32 v15, 16, v19
	v_bfe_u32 v18, v43, 16, 1
	v_bfe_u32 v19, v41, 16, 1
	v_and_or_b32 v15, v12, s39, v15
	v_and_or_b32 v14, v13, s39, v14
	v_and_or_b32 v13, v17, s39, v21
	v_and_or_b32 v12, v16, s39, v20
	v_add3_u32 v20, v41, v19, s38
	v_add3_u32 v21, v43, v18, s38
	v_bfe_u32 v18, v40, 16, 1
	v_bfe_u32 v19, v42, 16, 1
	v_bfe_u32 v22, v44, 16, 1
	v_bfe_u32 v23, v46, 16, 1
	v_bfe_u32 v16, v47, 16, 1
	v_bfe_u32 v17, v45, 16, 1
	v_add3_u32 v23, v46, v23, s38
	v_add3_u32 v22, v44, v22, s38
	v_add3_u32 v19, v42, v19, s38
	v_add3_u32 v18, v40, v18, s38
	v_add3_u32 v17, v45, v17, s38
	v_add3_u32 v16, v47, v16, s38
	v_lshrrev_b32_e32 v24, 16, v18
	v_lshrrev_b32_e32 v25, 16, v19
	v_lshrrev_b32_e32 v18, 16, v22
	v_lshrrev_b32_e32 v19, 16, v23
	v_bfe_u32 v22, v51, 16, 1
	v_bfe_u32 v23, v49, 16, 1
	v_and_or_b32 v19, v16, s39, v19
	v_and_or_b32 v18, v17, s39, v18
	v_and_or_b32 v17, v21, s39, v25
	v_and_or_b32 v16, v20, s39, v24
	v_add3_u32 v24, v49, v23, s38
	v_add3_u32 v25, v51, v22, s38
	v_bfe_u32 v22, v48, 16, 1
	v_bfe_u32 v23, v50, 16, 1
	v_bfe_u32 v26, v52, 16, 1
	v_bfe_u32 v27, v54, 16, 1
	v_bfe_u32 v20, v55, 16, 1
	v_bfe_u32 v21, v53, 16, 1
	v_add3_u32 v27, v54, v27, s38
	v_add3_u32 v26, v52, v26, s38
	v_add3_u32 v23, v50, v23, s38
	v_add3_u32 v22, v48, v22, s38
	v_add3_u32 v21, v53, v21, s38
	v_add3_u32 v20, v55, v20, s38
	v_lshrrev_b32_e32 v28, 16, v22
	v_lshrrev_b32_e32 v29, 16, v23
	v_lshrrev_b32_e32 v22, 16, v26
	v_lshrrev_b32_e32 v23, 16, v27
	v_bfe_u32 v26, v59, 16, 1
	v_bfe_u32 v27, v57, 16, 1
	v_and_or_b32 v23, v20, s39, v23
	v_and_or_b32 v22, v21, s39, v22
	v_and_or_b32 v21, v25, s39, v29
	v_and_or_b32 v20, v24, s39, v28
	v_add3_u32 v28, v57, v27, s38
	v_add3_u32 v29, v59, v26, s38
	v_bfe_u32 v26, v56, 16, 1
	v_bfe_u32 v27, v58, 16, 1
	v_bfe_u32 v30, v60, 16, 1
	v_bfe_u32 v31, v62, 16, 1
	v_bfe_u32 v24, v63, 16, 1
	v_bfe_u32 v25, v61, 16, 1
	v_add3_u32 v31, v62, v31, s38
	v_add3_u32 v30, v60, v30, s38
	v_add3_u32 v27, v58, v27, s38
	v_add3_u32 v26, v56, v26, s38
	v_div_scale_f32 v38, s[24:25], v72, v72, 1.0
	v_add3_u32 v25, v61, v25, s38
	v_add3_u32 v24, v63, v24, s38
	v_lshrrev_b32_e32 v32, 16, v26
	v_lshrrev_b32_e32 v33, 16, v27
	v_lshrrev_b32_e32 v26, 16, v30
	v_lshrrev_b32_e32 v27, 16, v31
	v_bfe_u32 v30, v67, 16, 1
	v_bfe_u32 v31, v65, 16, 1
	v_rcp_f32_e32 v39, v38
	v_and_or_b32 v27, v24, s39, v27
	v_and_or_b32 v26, v25, s39, v26
	v_and_or_b32 v25, v29, s39, v33
	v_and_or_b32 v24, v28, s39, v32
	v_add3_u32 v32, v65, v31, s38
	v_add3_u32 v33, v67, v30, s38
	v_bfe_u32 v30, v64, 16, 1
	v_bfe_u32 v31, v66, 16, 1
	v_bfe_u32 v35, v70, 16, 1
	v_bfe_u32 v28, v71, 16, 1
	v_add3_u32 v35, v70, v35, s38
	v_add3_u32 v31, v66, v31, s38
	v_add3_u32 v30, v64, v30, s38
	v_add3_u32 v28, v71, v28, s38
	v_bfe_u32 v34, v68, 16, 1
	v_lshrrev_b32_e32 v36, 16, v30
	v_lshrrev_b32_e32 v37, 16, v31
	v_lshrrev_b32_e32 v31, 16, v35
	v_bfe_u32 v29, v69, 16, 1
	v_add3_u32 v34, v68, v34, s38
	v_and_or_b32 v31, v28, s39, v31
	v_and_or_b32 v28, v32, s39, v36
	v_fma_f32 v32, -v38, v39, 1.0
	v_add3_u32 v29, v69, v29, s38
	v_lshrrev_b32_e32 v30, 16, v34
	v_fmac_f32_e32 v39, v32, v39
	v_div_scale_f32 v32, vcc, 1.0, v72, 1.0
	v_and_or_b32 v30, v29, s39, v30
	v_and_or_b32 v29, v33, s39, v37
	v_mul_f32_e32 v33, v32, v39
	v_fma_f32 v34, -v38, v33, v32
	v_fmac_f32_e32 v33, v34, v39
	ds_read_b64 v[34:35], v148
	v_fma_f32 v32, -v38, v33, v32
	v_div_fmas_f32 v32, v32, v39, v33
	v_div_fixup_f32 v32, v32, v72, 1.0
	v_mov_b32_e32 v33, v32
	s_waitcnt lgkmcnt(0)
	v_lshl_add_u64 v[34:35], v[34:35], 0, s[0:1]
	v_lshl_add_u64 v[34:35], v[34:35], 0, v[140:141]
	s_mov_b64 s[24:25], 0
	v_mov_b64_e32 v[36:37], v[94:95]

; #define MFMA(a, b, c) __builtin_amdgcn_mfma_f32_16x16x32_bf16((a), (b), (c), 0, 0, 0)
; template <int MODE, int K>
; DI void gemm_tile128(const Params& p, const u16* __restrict__ A, int lda, const u16* __restrict__ Bt, int tm, int tn,
;                           char* smem) {
;     ...
;     const char* sa = smem + (k & 1) * 32768;
;     const char* sb = sa + 16384;
; #pragma unroll
;     for (int ks = 0; ks < 2; ++ks) {
;       bf16x8 af[4], bfr[4];
; #pragma unroll
;       for (int i = 0; i < 4; ++i) {
;         af[i] = *(const bf16x8*)(sa + ((wm * 4 + i) * 2 + ks) * 1024 + frag_off);
;         bfr[i] = *(const bf16x8*)(sb + ((wn * 4 + i) * 2 + ks) * 1024 + frag_off);
;       }
;       __builtin_amdgcn_s_setprio(1);
; #pragma unroll
;       for (int mt = 0; mt < 4; ++mt)
; #pragma unroll
;         for (int nt = 0; nt < 4; ++nt) acc[mt][nt] = MFMA(bfr[nt], af[mt], acc[mt][nt]);
;       __builtin_amdgcn_s_setprio(0);
;     }
.LBB0_955:
	ds_read_b128 v[72:75], v162 offset:32768
	ds_read_b128 v[76:79], v162 offset:34816
	ds_read_b128 v[100:103], v164 offset:49152
	ds_read_b128 v[104:107], v164 offset:51200
	ds_read_b128 v[108:111], v162 offset:36864
	ds_read_b128 v[112:115], v162 offset:38912
	ds_read_b128 v[116:119], v164 offset:53248
	ds_read_b128 v[120:123], v164 offset:55296
	s_setprio 1
	s_waitcnt lgkmcnt(0)
	v_mfma_f32_16x16x32_bf16 v[0:3], v[100:103], v[72:75], v[0:3]
	v_mfma_f32_16x16x32_bf16 v[4:7], v[104:107], v[72:75], v[4:7]
	v_mfma_f32_16x16x32_bf16 v[8:11], v[116:119], v[72:75], v[8:11]
	v_mfma_f32_16x16x32_bf16 v[12:15], v[120:123], v[72:75], v[12:15]
	v_mfma_f32_16x16x32_bf16 v[16:19], v[100:103], v[76:79], v[16:19]
	v_mfma_f32_16x16x32_bf16 v[20:23], v[104:107], v[76:79], v[20:23]
	v_mfma_f32_16x16x32_bf16 v[24:27], v[116:119], v[76:79], v[24:27]
	v_mfma_f32_16x16x32_bf16 v[28:31], v[120:123], v[76:79], v[28:31]
	v_mfma_f32_16x16x32_bf16 v[72:75], v[100:103], v[108:111], v[32:35]
	v_mfma_f32_16x16x32_bf16 v[76:79], v[104:107], v[108:111], v[36:39]
	v_mfma_f32_16x16x32_bf16 v[124:127], v[116:119], v[108:111], v[40:43]
	v_mfma_f32_16x16x32_bf16 v[108:111], v[120:123], v[108:111], v[44:47]
	v_mfma_f32_16x16x32_bf16 v[100:103], v[100:103], v[112:115], v[48:51]
	v_mfma_f32_16x16x32_bf16 v[104:107], v[104:107], v[112:115], v[52:55]
	v_mfma_f32_16x16x32_bf16 v[116:119], v[116:119], v[112:115], v[56:59]
	v_mfma_f32_16x16x32_bf16 v[112:115], v[120:123], v[112:115], v[60:63]
	s_setprio 0
	ds_read_b128 v[32:35], v162 offset:33792
	ds_read_b128 v[120:123], v162 offset:35840
	ds_read_b128 v[144:147], v164 offset:50176
	ds_read_b128 v[148:151], v164 offset:52224
	ds_read_b128 v[152:155], v162 offset:37888
	ds_read_b128 v[156:159], v162 offset:39936
	ds_read_b128 v[166:169], v164 offset:54272
	ds_read_b128 v[192:195], v164 offset:56320
	s_setprio 1
	s_waitcnt lgkmcnt(5)
	v_mfma_f32_16x16x32_bf16 v[60:63], v[144:147], v[32:35], v[0:3]
	s_waitcnt lgkmcnt(4)
	v_mfma_f32_16x16x32_bf16 v[56:59], v[148:151], v[32:35], v[4:7]
	s_waitcnt lgkmcnt(1)
	v_mfma_f32_16x16x32_bf16 v[52:55], v[166:169], v[32:35], v[8:11]
	s_waitcnt lgkmcnt(0)
	v_mfma_f32_16x16x32_bf16 v[48:51], v[192:195], v[32:35], v[12:15]
	v_mfma_f32_16x16x32_bf16 v[44:47], v[144:147], v[120:123], v[16:19]
	v_mfma_f32_16x16x32_bf16 v[40:43], v[148:151], v[120:123], v[20:23]
	v_mfma_f32_16x16x32_bf16 v[36:39], v[166:169], v[120:123], v[24:27]
	v_mfma_f32_16x16x32_bf16 v[32:35], v[192:195], v[120:123], v[28:31]
	v_mfma_f32_16x16x32_bf16 v[28:31], v[144:147], v[152:155], v[72:75]
	v_mfma_f32_16x16x32_bf16 v[24:27], v[148:151], v[152:155], v[76:79]
	v_mfma_f32_16x16x32_bf16 v[20:23], v[166:169], v[152:155], v[124:127]
	v_mfma_f32_16x16x32_bf16 v[16:19], v[192:195], v[152:155], v[108:111]
	v_mfma_f32_16x16x32_bf16 v[12:15], v[144:147], v[156:159], v[100:103]
	v_mfma_f32_16x16x32_bf16 v[8:11], v[148:151], v[156:159], v[104:107]
	v_mfma_f32_16x16x32_bf16 v[4:7], v[166:169], v[156:159], v[116:119]
	v_mfma_f32_16x16x32_bf16 v[0:3], v[192:195], v[156:159], v[112:115]
	s_setprio 0
	s_add_u32 s14, s14, 0x100
	s_addc_u32 s15, s15, 0
	s_cmpk_eq_i32 s14, 0x800
	s_cbranch_scc1 .LBB0_958
; #define MFMA(a, b, c) __builtin_amdgcn_mfma_f32_16x16x32_bf16((a), (b), (c), 0, 0, 0)
; #define AS1 __attribute__((address_space(1)))
; #define AS3 __attribute__((address_space(3)))
; template <int MODE, int K>
; DI void gemm_tile128(const Params& p, const u16* __restrict__ A, int lda, const u16* __restrict__ Bt, int tm, int tn,
;                           char* smem) {
;     ...
; #pragma unroll 2
;   for (int k = 0; k < K / 64; ++k) {
;     __syncthreads();
;     if (k + 1 < K / 64) {
;       char* st = smem + ((k + 1) & 1) * 32768;
; #pragma unroll
;       for (int i = 0; i < 4; ++i) {
;         __builtin_amdgcn_global_load_lds((const unsigned AS1*)(gA[i] + (k + 1) * 64), (unsigned AS3*)(st + (w * 4 + i) * 1024), 16, 0, 0);
;         __builtin_amdgcn_global_load_lds((const unsigned AS1*)(gB[i] + (k + 1) * 64), (unsigned AS3*)(st + 16384 + (w * 4 + i) * 1024), 16, 0, 0);
;       }
;     }
;     const char* sa = smem + (k & 1) * 32768;
;     const char* sb = sa + 16384;
; #pragma unroll
;     for (int ks = 0; ks < 2; ++ks) {
;       bf16x8 af[4], bfr[4];
; #pragma unroll
;       for (int i = 0; i < 4; ++i) {
;         af[i] = *(const bf16x8*)(sa + ((wm * 4 + i) * 2 + ks) * 1024 + frag_off);
;         bfr[i] = *(const bf16x8*)(sb + ((wn * 4 + i) * 2 + ks) * 1024 + frag_off);
;       }
;       __builtin_amdgcn_s_setprio(1);
; #pragma unroll
;       for (int mt = 0; mt < 4; ++mt)
; #pragma unroll
;         for (int nt = 0; nt < 4; ++nt) acc[mt][nt] = MFMA(bfr[nt], af[mt], acc[mt][nt]);
;       __builtin_amdgcn_s_setprio(0);
;     }
.LBB0_956:
	v_lshl_add_u64 v[72:73], v[70:71], 0, s[14:15]
	v_readfirstlane_b32 s22, v89
	v_lshl_add_u64 v[74:75], v[72:73], 0, s[0:1]
	s_mov_b32 m0, s22
	s_waitcnt vmcnt(0) lgkmcnt(0)
	s_barrier
	global_load_lds_dwordx4 v[74:75], off
	v_lshl_add_u64 v[74:75], v[68:69], 0, s[14:15]
	v_readfirstlane_b32 s22, v90
	v_lshl_add_u64 v[76:77], v[74:75], 0, s[0:1]
	s_mov_b32 m0, s22
	v_readfirstlane_b32 s22, v91
	global_load_lds_dwordx4 v[76:77], off
	v_lshl_add_u64 v[76:77], v[72:73], 0, s[2:3]
	s_mov_b32 m0, s22
	v_readfirstlane_b32 s22, v92
	global_load_lds_dwordx4 v[76:77], off
	v_lshl_add_u64 v[76:77], v[74:75], 0, s[2:3]
	s_mov_b32 m0, s22
	v_readfirstlane_b32 s22, v93
	global_load_lds_dwordx4 v[76:77], off
	v_lshl_add_u64 v[76:77], v[66:67], 0, s[14:15]
	v_lshl_add_u64 v[78:79], v[76:77], 0, s[0:1]
	s_mov_b32 m0, s22
	v_readfirstlane_b32 s22, v94
	global_load_lds_dwordx4 v[78:79], off
	v_lshl_add_u64 v[78:79], v[64:65], 0, s[14:15]
	v_lshl_add_u64 v[100:101], v[78:79], 0, s[0:1]
	s_mov_b32 m0, s22
	v_readfirstlane_b32 s22, v95
	global_load_lds_dwordx4 v[100:101], off
	v_lshl_add_u64 v[100:101], v[76:77], 0, s[2:3]
	s_mov_b32 m0, s22
	v_readfirstlane_b32 s22, v96
	global_load_lds_dwordx4 v[100:101], off
	v_lshl_add_u64 v[100:101], v[78:79], 0, s[2:3]
	s_mov_b32 m0, s22
	s_nop 0
	global_load_lds_dwordx4 v[100:101], off
	ds_read_b128 v[100:103], v162
	ds_read_b128 v[104:107], v162 offset:2048
	ds_read_b128 v[108:111], v164 offset:16384
	ds_read_b128 v[112:115], v164 offset:18432
	ds_read_b128 v[116:119], v162 offset:4096
	ds_read_b128 v[120:123], v162 offset:6144
	ds_read_b128 v[124:127], v164 offset:20480
	ds_read_b128 v[144:147], v164 offset:22528
	s_setprio 1
	s_waitcnt lgkmcnt(0)
	v_mfma_f32_16x16x32_bf16 v[60:63], v[108:111], v[100:103], v[60:63]
	v_mfma_f32_16x16x32_bf16 v[56:59], v[112:115], v[100:103], v[56:59]
	v_mfma_f32_16x16x32_bf16 v[52:55], v[124:127], v[100:103], v[52:55]
	v_mfma_f32_16x16x32_bf16 v[48:51], v[144:147], v[100:103], v[48:51]
	v_mfma_f32_16x16x32_bf16 v[44:47], v[108:111], v[104:107], v[44:47]
	v_mfma_f32_16x16x32_bf16 v[40:43], v[112:115], v[104:107], v[40:43]
	v_mfma_f32_16x16x32_bf16 v[36:39], v[124:127], v[104:107], v[36:39]
	v_mfma_f32_16x16x32_bf16 v[32:35], v[144:147], v[104:107], v[32:35]
	v_mfma_f32_16x16x32_bf16 v[100:103], v[108:111], v[116:119], v[28:31]
	v_mfma_f32_16x16x32_bf16 v[104:107], v[112:115], v[116:119], v[24:27]
	v_mfma_f32_16x16x32_bf16 v[148:151], v[124:127], v[116:119], v[20:23]
	v_mfma_f32_16x16x32_bf16 v[116:119], v[144:147], v[116:119], v[16:19]
	v_mfma_f32_16x16x32_bf16 v[108:111], v[108:111], v[120:123], v[12:15]
	v_mfma_f32_16x16x32_bf16 v[112:115], v[112:115], v[120:123], v[8:11]
	v_mfma_f32_16x16x32_bf16 v[124:127], v[124:127], v[120:123], v[4:7]
	v_mfma_f32_16x16x32_bf16 v[120:123], v[144:147], v[120:123], v[0:3]
	s_setprio 0
	ds_read_b128 v[12:15], v162 offset:1024
	ds_read_b128 v[28:31], v162 offset:3072
	ds_read_b128 v[144:147], v164 offset:17408
	ds_read_b128 v[152:155], v164 offset:19456
	ds_read_b128 v[156:159], v162 offset:5120
	ds_read_b128 v[166:169], v162 offset:7168
	ds_read_b128 v[192:195], v164 offset:21504
	ds_read_b128 v[196:199], v164 offset:23552
	s_setprio 1
	s_waitcnt lgkmcnt(5)
	v_mfma_f32_16x16x32_bf16 v[0:3], v[144:147], v[12:15], v[60:63]
	s_waitcnt lgkmcnt(4)
	v_mfma_f32_16x16x32_bf16 v[4:7], v[152:155], v[12:15], v[56:59]
	s_waitcnt lgkmcnt(1)
	v_mfma_f32_16x16x32_bf16 v[8:11], v[192:195], v[12:15], v[52:55]
	s_waitcnt lgkmcnt(0)
	v_mfma_f32_16x16x32_bf16 v[12:15], v[196:199], v[12:15], v[48:51]
	v_mfma_f32_16x16x32_bf16 v[16:19], v[144:147], v[28:31], v[44:47]
	v_mfma_f32_16x16x32_bf16 v[20:23], v[152:155], v[28:31], v[40:43]
	v_mfma_f32_16x16x32_bf16 v[24:27], v[192:195], v[28:31], v[36:39]
	v_mfma_f32_16x16x32_bf16 v[28:31], v[196:199], v[28:31], v[32:35]
	v_mfma_f32_16x16x32_bf16 v[32:35], v[144:147], v[156:159], v[100:103]
	v_mfma_f32_16x16x32_bf16 v[36:39], v[152:155], v[156:159], v[104:107]
	v_mfma_f32_16x16x32_bf16 v[40:43], v[192:195], v[156:159], v[148:151]
	v_mfma_f32_16x16x32_bf16 v[44:47], v[196:199], v[156:159], v[116:119]
	v_mfma_f32_16x16x32_bf16 v[48:51], v[144:147], v[166:169], v[108:111]
	v_mfma_f32_16x16x32_bf16 v[52:55], v[152:155], v[166:169], v[112:115]
	v_mfma_f32_16x16x32_bf16 v[56:59], v[192:195], v[166:169], v[124:127]
	v_mfma_f32_16x16x32_bf16 v[60:63], v[196:199], v[166:169], v[120:123]
	s_setprio 0
	s_cmpk_eq_i32 s14, 0x700
	s_waitcnt vmcnt(0)
	s_barrier
	s_cbranch_scc1 .LBB0_955
	v_readfirstlane_b32 s22, v179
	v_lshl_add_u64 v[100:101], v[72:73], 0, s[10:11]
	s_mov_b32 m0, s22
	v_readfirstlane_b32 s22, v82
	global_load_lds_dwordx4 v[100:101], off
	v_lshl_add_u64 v[100:101], v[74:75], 0, s[10:11]
	s_mov_b32 m0, s22
	v_readfirstlane_b32 s22, v83
	global_load_lds_dwordx4 v[100:101], off
	v_lshl_add_u64 v[72:73], v[72:73], 0, s[12:13]
	s_mov_b32 m0, s22
	v_readfirstlane_b32 s22, v84
	global_load_lds_dwordx4 v[72:73], off
	v_lshl_add_u64 v[72:73], v[74:75], 0, s[12:13]
	s_mov_b32 m0, s22
	v_readfirstlane_b32 s22, v85
	global_load_lds_dwordx4 v[72:73], off
	v_lshl_add_u64 v[72:73], v[76:77], 0, s[10:11]
	s_mov_b32 m0, s22
	v_readfirstlane_b32 s22, v86
	global_load_lds_dwordx4 v[72:73], off
	v_lshl_add_u64 v[72:73], v[78:79], 0, s[10:11]
	s_mov_b32 m0, s22
	v_readfirstlane_b32 s22, v87
	global_load_lds_dwordx4 v[72:73], off
	v_lshl_add_u64 v[72:73], v[76:77], 0, s[12:13]
	s_mov_b32 m0, s22
	v_readfirstlane_b32 s22, v88
	global_load_lds_dwordx4 v[72:73], off
	v_lshl_add_u64 v[72:73], v[78:79], 0, s[12:13]
	s_mov_b32 m0, s22
	s_nop 0
	global_load_lds_dwordx4 v[72:73], off
	s_branch .LBB0_955

; #define MFMA(a, b, c) __builtin_amdgcn_mfma_f32_16x16x32_bf16((a), (b), (c), 0, 0, 0)
; template <int MODE, int K>
; DI void gemm_tile(const Params& p, const u16* __restrict__ A, int lda, const u16* __restrict__ Bt, int tm, int tn,
;                           char* smem) {
;     ...
;     const char* sa = smem + (k & 1) * 24576;
;     const char* sb = sa + 16384;
;     bf16x8 af[8], bfr[4];
; #pragma unroll
;     for (int i = 0; i < 8; ++i) af[i] = *(const bf16x8*)(sa + (wm * 8 + i) * 1024 + frag_off);
; #pragma unroll
;     for (int i = 0; i < 4; ++i) bfr[i] = *(const bf16x8*)(sb + (wn * 4 + i) * 1024 + frag_off);
;     __builtin_amdgcn_s_setprio(1);
; #pragma unroll
;     for (int mt = 0; mt < 8; ++mt)
; #pragma unroll
;       for (int nt = 0; nt < 4; ++nt) acc[mt][nt] = MFMA(bfr[nt], af[mt], acc[mt][nt]);
;     __builtin_amdgcn_s_setprio(0);
;   }
.LBB0_1017:
	ds_read_b128 v[150:153], v188 offset:24576
	ds_read_b128 v[154:157], v188 offset:25600
	ds_read_b128 v[158:161], v188 offset:26624
	ds_read_b128 v[202:205], v188 offset:27648
	ds_read_b128 v[206:209], v188 offset:28672
	ds_read_b128 v[210:213], v188 offset:29696
	ds_read_b128 v[214:217], v188 offset:30720
	ds_read_b128 v[218:221], v189 offset:24576
	ds_read_b128 v[222:225], v190 offset:40960
	ds_read_b128 v[226:229], v190 offset:41984
	ds_read_b128 v[230:233], v190 offset:43008
	ds_read_b128 v[234:237], v190 offset:44032
	s_setprio 1
	s_waitcnt lgkmcnt(0)
	v_mfma_f32_16x16x32_bf16 v[124:127], v[222:225], v[150:153], v[124:127]
	v_mfma_f32_16x16x32_bf16 v[120:123], v[226:229], v[150:153], v[120:123]
	v_mfma_f32_16x16x32_bf16 v[116:119], v[230:233], v[150:153], v[116:119]
	v_mfma_f32_16x16x32_bf16 v[112:115], v[234:237], v[150:153], v[112:115]
	v_mfma_f32_16x16x32_bf16 v[108:111], v[222:225], v[154:157], v[108:111]
	v_mfma_f32_16x16x32_bf16 v[104:107], v[226:229], v[154:157], v[104:107]
	v_mfma_f32_16x16x32_bf16 v[100:103], v[230:233], v[154:157], v[100:103]
	v_mfma_f32_16x16x32_bf16 v[96:99], v[234:237], v[154:157], v[96:99]
	v_mfma_f32_16x16x32_bf16 v[92:95], v[222:225], v[158:161], v[92:95]
	v_mfma_f32_16x16x32_bf16 v[88:91], v[226:229], v[158:161], v[88:91]
	v_mfma_f32_16x16x32_bf16 v[84:87], v[230:233], v[158:161], v[84:87]
	v_mfma_f32_16x16x32_bf16 v[80:83], v[234:237], v[158:161], v[80:83]
	v_mfma_f32_16x16x32_bf16 v[68:71], v[222:225], v[202:205], v[68:71]
	v_mfma_f32_16x16x32_bf16 v[64:67], v[226:229], v[202:205], v[64:67]
	v_mfma_f32_16x16x32_bf16 v[72:75], v[230:233], v[202:205], v[72:75]
	v_mfma_f32_16x16x32_bf16 v[76:79], v[234:237], v[202:205], v[76:79]
	v_mfma_f32_16x16x32_bf16 v[48:51], v[222:225], v[206:209], v[48:51]
	v_mfma_f32_16x16x32_bf16 v[52:55], v[226:229], v[206:209], v[52:55]
	v_mfma_f32_16x16x32_bf16 v[56:59], v[230:233], v[206:209], v[56:59]
	v_mfma_f32_16x16x32_bf16 v[60:63], v[234:237], v[206:209], v[60:63]
	v_mfma_f32_16x16x32_bf16 v[32:35], v[222:225], v[210:213], v[32:35]
	v_mfma_f32_16x16x32_bf16 v[36:39], v[226:229], v[210:213], v[36:39]
	v_mfma_f32_16x16x32_bf16 v[40:43], v[230:233], v[210:213], v[40:43]
	v_mfma_f32_16x16x32_bf16 v[44:47], v[234:237], v[210:213], v[44:47]
	v_mfma_f32_16x16x32_bf16 v[16:19], v[222:225], v[214:217], v[16:19]
	v_mfma_f32_16x16x32_bf16 v[20:23], v[226:229], v[214:217], v[20:23]
	v_mfma_f32_16x16x32_bf16 v[24:27], v[230:233], v[214:217], v[24:27]
	v_mfma_f32_16x16x32_bf16 v[28:31], v[234:237], v[214:217], v[28:31]
	v_mfma_f32_16x16x32_bf16 v[0:3], v[222:225], v[218:221], v[0:3]
	v_mfma_f32_16x16x32_bf16 v[4:7], v[226:229], v[218:221], v[4:7]
	v_mfma_f32_16x16x32_bf16 v[8:11], v[230:233], v[218:221], v[8:11]
	v_mfma_f32_16x16x32_bf16 v[12:15], v[234:237], v[218:221], v[12:15]
	s_setprio 0
	s_add_u32 s2, s2, 0x80
	s_addc_u32 s3, s3, 0
	s_cmpk_eq_i32 s2, 0x800
	s_cbranch_scc1 .LBB0_1020
; #define MFMA(a, b, c) __builtin_amdgcn_mfma_f32_16x16x32_bf16((a), (b), (c), 0, 0, 0)
; #define AS1 __attribute__((address_space(1)))
; #define AS3 __attribute__((address_space(3)))
; template <int MODE, int K>
; DI void gemm_tile(const Params& p, const u16* __restrict__ A, int lda, const u16* __restrict__ Bt, int tm, int tn,
;                           char* smem) {
;     ...
; #pragma unroll 2
;   for (int k = 0; k < K / 32; ++k) {
;     __syncthreads();
;     if (k + 1 < K / 32) {
;       char* st = smem + ((k + 1) & 1) * 24576;
; #pragma unroll
;       for (int i = 0; i < 4; ++i)
;         __builtin_amdgcn_global_load_lds((const unsigned AS1*)(gA[i] + (k + 1) * 32), (unsigned AS3*)(st + (w * 4 + i) * 1024), 16, 0, 0);
; #pragma unroll
;       for (int i = 0; i < 2; ++i)
;         __builtin_amdgcn_global_load_lds((const unsigned AS1*)(gB[i] + (k + 1) * 32), (unsigned AS3*)(st + 16384 + (w * 2 + i) * 1024), 16, 0, 0);
;     }
;     const char* sa = smem + (k & 1) * 24576;
;     const char* sb = sa + 16384;
;     bf16x8 af[8], bfr[4];
; #pragma unroll
;     for (int i = 0; i < 8; ++i) af[i] = *(const bf16x8*)(sa + (wm * 8 + i) * 1024 + frag_off);
; #pragma unroll
;     for (int i = 0; i < 4; ++i) bfr[i] = *(const bf16x8*)(sb + (wn * 4 + i) * 1024 + frag_off);
;     __builtin_amdgcn_s_setprio(1);
; #pragma unroll
;     for (int mt = 0; mt < 8; ++mt)
; #pragma unroll
;       for (int nt = 0; nt < 4; ++nt) acc[mt][nt] = MFMA(bfr[nt], af[mt], acc[mt][nt]);
;     __builtin_amdgcn_s_setprio(0);
;   }
.LBB0_1018:
	v_lshl_add_u64 v[150:151], v[148:149], 0, s[2:3]
	v_readfirstlane_b32 s16, v192
	v_lshl_add_u64 v[152:153], v[150:151], 0, 64
	s_mov_b32 m0, s16
	s_waitcnt vmcnt(0) lgkmcnt(0)
	s_barrier
	global_load_lds_dwordx4 v[152:153], off
	v_lshl_add_u64 v[152:153], v[146:147], 0, s[2:3]
	v_readfirstlane_b32 s16, v193
	v_lshl_add_u64 v[154:155], v[152:153], 0, 64
	s_mov_b32 m0, s16
	v_readfirstlane_b32 s16, v194
	global_load_lds_dwordx4 v[154:155], off
	v_lshl_add_u64 v[154:155], v[144:145], 0, s[2:3]
	v_lshl_add_u64 v[156:157], v[154:155], 0, 64
	s_mov_b32 m0, s16
	v_readfirstlane_b32 s16, v195
	global_load_lds_dwordx4 v[156:157], off
	v_lshl_add_u64 v[156:157], v[142:143], 0, s[2:3]
	v_lshl_add_u64 v[158:159], v[156:157], 0, 64
	s_mov_b32 m0, s16
	v_readfirstlane_b32 s16, v196
	global_load_lds_dwordx4 v[158:159], off
	v_lshl_add_u64 v[158:159], v[140:141], 0, s[2:3]
	v_lshl_add_u64 v[160:161], v[158:159], 0, 64
	s_mov_b32 m0, s16
	v_readfirstlane_b32 s16, v197
	global_load_lds_dwordx4 v[160:161], off
	v_lshl_add_u64 v[160:161], v[130:131], 0, s[2:3]
	v_lshl_add_u64 v[202:203], v[160:161], 0, 64
	s_mov_b32 m0, s16
	s_nop 0
	global_load_lds_dwordx4 v[202:203], off
	ds_read_b128 v[202:205], v188
	ds_read_b128 v[206:209], v188 offset:1024
	ds_read_b128 v[210:213], v188 offset:2048
	ds_read_b128 v[214:217], v188 offset:3072
	ds_read_b128 v[218:221], v188 offset:4096
	ds_read_b128 v[222:225], v188 offset:5120
	ds_read_b128 v[226:229], v188 offset:6144
	ds_read_b128 v[230:233], v189
	ds_read_b128 v[234:237], v190 offset:16384
	ds_read_b128 v[238:241], v190 offset:17408
	ds_read_b128 v[242:245], v190 offset:18432
	ds_read_b128 v[246:249], v190 offset:19456
	s_setprio 1
	s_waitcnt lgkmcnt(0)
	v_mfma_f32_16x16x32_bf16 v[124:127], v[234:237], v[202:205], v[124:127]
	v_mfma_f32_16x16x32_bf16 v[120:123], v[238:241], v[202:205], v[120:123]
	v_mfma_f32_16x16x32_bf16 v[116:119], v[242:245], v[202:205], v[116:119]
	v_mfma_f32_16x16x32_bf16 v[112:115], v[246:249], v[202:205], v[112:115]
	v_mfma_f32_16x16x32_bf16 v[108:111], v[234:237], v[206:209], v[108:111]
	v_mfma_f32_16x16x32_bf16 v[104:107], v[238:241], v[206:209], v[104:107]
	v_mfma_f32_16x16x32_bf16 v[100:103], v[242:245], v[206:209], v[100:103]
	v_mfma_f32_16x16x32_bf16 v[96:99], v[246:249], v[206:209], v[96:99]
	v_mfma_f32_16x16x32_bf16 v[92:95], v[234:237], v[210:213], v[92:95]
	v_mfma_f32_16x16x32_bf16 v[88:91], v[238:241], v[210:213], v[88:91]
	v_mfma_f32_16x16x32_bf16 v[84:87], v[242:245], v[210:213], v[84:87]
	v_mfma_f32_16x16x32_bf16 v[80:83], v[246:249], v[210:213], v[80:83]
	v_mfma_f32_16x16x32_bf16 v[68:71], v[234:237], v[214:217], v[68:71]
	v_mfma_f32_16x16x32_bf16 v[64:67], v[238:241], v[214:217], v[64:67]
	v_mfma_f32_16x16x32_bf16 v[72:75], v[242:245], v[214:217], v[72:75]
	v_mfma_f32_16x16x32_bf16 v[76:79], v[246:249], v[214:217], v[76:79]
	v_mfma_f32_16x16x32_bf16 v[48:51], v[234:237], v[218:221], v[48:51]
	v_mfma_f32_16x16x32_bf16 v[52:55], v[238:241], v[218:221], v[52:55]
	v_mfma_f32_16x16x32_bf16 v[56:59], v[242:245], v[218:221], v[56:59]
	v_mfma_f32_16x16x32_bf16 v[60:63], v[246:249], v[218:221], v[60:63]
	v_mfma_f32_16x16x32_bf16 v[32:35], v[234:237], v[222:225], v[32:35]
	v_mfma_f32_16x16x32_bf16 v[36:39], v[238:241], v[222:225], v[36:39]
	v_mfma_f32_16x16x32_bf16 v[40:43], v[242:245], v[222:225], v[40:43]
	v_mfma_f32_16x16x32_bf16 v[44:47], v[246:249], v[222:225], v[44:47]
	v_mfma_f32_16x16x32_bf16 v[16:19], v[234:237], v[226:229], v[16:19]
	v_mfma_f32_16x16x32_bf16 v[20:23], v[238:241], v[226:229], v[20:23]
	v_mfma_f32_16x16x32_bf16 v[24:27], v[242:245], v[226:229], v[24:27]
	v_mfma_f32_16x16x32_bf16 v[28:31], v[246:249], v[226:229], v[28:31]
	v_mfma_f32_16x16x32_bf16 v[0:3], v[234:237], v[230:233], v[0:3]
	v_mfma_f32_16x16x32_bf16 v[4:7], v[238:241], v[230:233], v[4:7]
	v_mfma_f32_16x16x32_bf16 v[8:11], v[242:245], v[230:233], v[8:11]
	v_mfma_f32_16x16x32_bf16 v[12:15], v[246:249], v[230:233], v[12:15]
	s_setprio 0
	s_cmpk_eq_i32 s2, 0x780
	s_waitcnt vmcnt(0)
	s_barrier
	s_cbranch_scc1 .LBB0_1017
	v_readfirstlane_b32 s16, v179
	v_lshl_add_u64 v[150:151], v[150:151], 0, s[0:1]
	s_mov_b32 m0, s16
	v_readfirstlane_b32 s16, v168
	global_load_lds_dwordx4 v[150:151], off
	v_lshl_add_u64 v[150:151], v[152:153], 0, s[0:1]
	s_mov_b32 m0, s16
	v_readfirstlane_b32 s16, v169
	global_load_lds_dwordx4 v[150:151], off
	v_lshl_add_u64 v[150:151], v[154:155], 0, s[0:1]
	s_mov_b32 m0, s16
	v_readfirstlane_b32 s16, v172
	global_load_lds_dwordx4 v[150:151], off
	v_lshl_add_u64 v[150:151], v[156:157], 0, s[0:1]
	s_mov_b32 m0, s16
	v_readfirstlane_b32 s16, v173
	global_load_lds_dwordx4 v[150:151], off
	v_lshl_add_u64 v[150:151], v[158:159], 0, s[0:1]
	s_mov_b32 m0, s16
	v_readfirstlane_b32 s16, v191
	global_load_lds_dwordx4 v[150:151], off
	v_lshl_add_u64 v[150:151], v[160:161], 0, s[0:1]
	s_mov_b32 m0, s16
	s_nop 0
	global_load_lds_dwordx4 v[150:151], off
	s_branch .LBB0_1017

; #define MFMA(a, b, c) __builtin_amdgcn_mfma_f32_16x16x32_bf16((a), (b), (c), 0, 0, 0)
; template <int MODE, int K>
; DI void gemm_tile128(const Params& p, const u16* __restrict__ A, int lda, const u16* __restrict__ Bt, int tm, int tn,
;                           char* smem) {
;     ...
;     const char* sa = smem + (k & 1) * 32768;
;     const char* sb = sa + 16384;
; #pragma unroll
;     for (int ks = 0; ks < 2; ++ks) {
;       bf16x8 af[4], bfr[4];
; #pragma unroll
;       for (int i = 0; i < 4; ++i) {
;         af[i] = *(const bf16x8*)(sa + ((wm * 4 + i) * 2 + ks) * 1024 + frag_off);
;         bfr[i] = *(const bf16x8*)(sb + ((wn * 4 + i) * 2 + ks) * 1024 + frag_off);
;       }
;       __builtin_amdgcn_s_setprio(1);
; #pragma unroll
;       for (int mt = 0; mt < 4; ++mt)
; #pragma unroll
;         for (int nt = 0; nt < 4; ++nt) acc[mt][nt] = MFMA(bfr[nt], af[mt], acc[mt][nt]);
;       __builtin_amdgcn_s_setprio(0);
;     }
.LBB0_1040:
	ds_read_b128 v[100:103], v162 offset:32768
	ds_read_b128 v[104:107], v162 offset:34816
	ds_read_b128 v[140:143], v164 offset:49152
	ds_read_b128 v[144:147], v164 offset:51200
	ds_read_b128 v[148:151], v162 offset:36864
	ds_read_b128 v[152:155], v162 offset:38912
	ds_read_b128 v[156:159], v164 offset:53248
	ds_read_b128 v[166:169], v164 offset:55296
	s_setprio 1
	s_waitcnt lgkmcnt(0)
	v_mfma_f32_16x16x32_bf16 v[0:3], v[140:143], v[100:103], v[0:3]
	v_mfma_f32_16x16x32_bf16 v[4:7], v[144:147], v[100:103], v[4:7]
	v_mfma_f32_16x16x32_bf16 v[8:11], v[156:159], v[100:103], v[8:11]
	v_mfma_f32_16x16x32_bf16 v[12:15], v[166:169], v[100:103], v[12:15]
	v_mfma_f32_16x16x32_bf16 v[16:19], v[140:143], v[104:107], v[16:19]
	v_mfma_f32_16x16x32_bf16 v[20:23], v[144:147], v[104:107], v[20:23]
	v_mfma_f32_16x16x32_bf16 v[24:27], v[156:159], v[104:107], v[24:27]
	v_mfma_f32_16x16x32_bf16 v[28:31], v[166:169], v[104:107], v[28:31]
	v_mfma_f32_16x16x32_bf16 v[100:103], v[140:143], v[148:151], v[32:35]
	v_mfma_f32_16x16x32_bf16 v[104:107], v[144:147], v[148:151], v[36:39]
	v_mfma_f32_16x16x32_bf16 v[182:185], v[156:159], v[148:151], v[40:43]
	v_mfma_f32_16x16x32_bf16 v[148:151], v[166:169], v[148:151], v[44:47]
	v_mfma_f32_16x16x32_bf16 v[140:143], v[140:143], v[152:155], v[48:51]
	v_mfma_f32_16x16x32_bf16 v[144:147], v[144:147], v[152:155], v[52:55]
	v_mfma_f32_16x16x32_bf16 v[156:159], v[156:159], v[152:155], v[56:59]
	v_mfma_f32_16x16x32_bf16 v[152:155], v[166:169], v[152:155], v[60:63]
	s_setprio 0
	ds_read_b128 v[32:35], v162 offset:33792
	ds_read_b128 v[166:169], v162 offset:35840
	ds_read_b128 v[186:189], v164 offset:50176
	ds_read_b128 v[190:193], v164 offset:52224
	ds_read_b128 v[194:197], v162 offset:37888
	ds_read_b128 v[198:201], v162 offset:39936
	ds_read_b128 v[202:205], v164 offset:54272
	ds_read_b128 v[206:209], v164 offset:56320
	s_setprio 1
	s_waitcnt lgkmcnt(5)
	v_mfma_f32_16x16x32_bf16 v[60:63], v[186:189], v[32:35], v[0:3]
	s_waitcnt lgkmcnt(4)
	v_mfma_f32_16x16x32_bf16 v[56:59], v[190:193], v[32:35], v[4:7]
	s_waitcnt lgkmcnt(1)
	v_mfma_f32_16x16x32_bf16 v[52:55], v[202:205], v[32:35], v[8:11]
	s_waitcnt lgkmcnt(0)
	v_mfma_f32_16x16x32_bf16 v[48:51], v[206:209], v[32:35], v[12:15]
	v_mfma_f32_16x16x32_bf16 v[44:47], v[186:189], v[166:169], v[16:19]
	v_mfma_f32_16x16x32_bf16 v[40:43], v[190:193], v[166:169], v[20:23]
	v_mfma_f32_16x16x32_bf16 v[36:39], v[202:205], v[166:169], v[24:27]
	v_mfma_f32_16x16x32_bf16 v[32:35], v[206:209], v[166:169], v[28:31]
	v_mfma_f32_16x16x32_bf16 v[16:19], v[186:189], v[194:197], v[100:103]
	v_mfma_f32_16x16x32_bf16 v[20:23], v[190:193], v[194:197], v[104:107]
	v_mfma_f32_16x16x32_bf16 v[24:27], v[202:205], v[194:197], v[182:185]
	v_mfma_f32_16x16x32_bf16 v[28:31], v[206:209], v[194:197], v[148:151]
	v_mfma_f32_16x16x32_bf16 v[0:3], v[186:189], v[198:201], v[140:143]
	v_mfma_f32_16x16x32_bf16 v[4:7], v[190:193], v[198:201], v[144:147]
	v_mfma_f32_16x16x32_bf16 v[8:11], v[202:205], v[198:201], v[156:159]
	v_mfma_f32_16x16x32_bf16 v[12:15], v[206:209], v[198:201], v[152:155]
	s_setprio 0
	s_add_u32 s24, s24, 0x100
	s_addc_u32 s25, s25, 0
	s_cmpk_lg_i32 s24, 0x800
	s_cbranch_scc0 .LBB0_1038
; #define MFMA(a, b, c) __builtin_amdgcn_mfma_f32_16x16x32_bf16((a), (b), (c), 0, 0, 0)
; #define AS1 __attribute__((address_space(1)))
; #define AS3 __attribute__((address_space(3)))
; template <int MODE, int K>
; DI void gemm_tile128(const Params& p, const u16* __restrict__ A, int lda, const u16* __restrict__ Bt, int tm, int tn,
;                           char* smem) {
;     ...
; #pragma unroll 2
;   for (int k = 0; k < K / 64; ++k) {
;     __syncthreads();
;     if (k + 1 < K / 64) {
;       char* st = smem + ((k + 1) & 1) * 32768;
; #pragma unroll
;       for (int i = 0; i < 4; ++i) {
;         __builtin_amdgcn_global_load_lds((const unsigned AS1*)(gA[i] + (k + 1) * 64), (unsigned AS3*)(st + (w * 4 + i) * 1024), 16, 0, 0);
;         __builtin_amdgcn_global_load_lds((const unsigned AS1*)(gB[i] + (k + 1) * 64), (unsigned AS3*)(st + 16384 + (w * 4 + i) * 1024), 16, 0, 0);
;       }
;     }
;     const char* sa = smem + (k & 1) * 32768;
;     const char* sb = sa + 16384;
; #pragma unroll
;     for (int ks = 0; ks < 2; ++ks) {
;       bf16x8 af[4], bfr[4];
; #pragma unroll
;       for (int i = 0; i < 4; ++i) {
;         af[i] = *(const bf16x8*)(sa + ((wm * 4 + i) * 2 + ks) * 1024 + frag_off);
;         bfr[i] = *(const bf16x8*)(sb + ((wn * 4 + i) * 2 + ks) * 1024 + frag_off);
;       }
;       __builtin_amdgcn_s_setprio(1);
; #pragma unroll
;       for (int mt = 0; mt < 4; ++mt)
; #pragma unroll
;         for (int nt = 0; nt < 4; ++nt) acc[mt][nt] = MFMA(bfr[nt], af[mt], acc[mt][nt]);
;       __builtin_amdgcn_s_setprio(0);
;     }
.LBB0_1041:
	v_lshl_add_u64 v[100:101], v[96:97], 0, s[24:25]
	v_readfirstlane_b32 s31, v117
	v_lshl_add_u64 v[102:103], v[100:101], 0, s[4:5]
	s_mov_b32 m0, s31
	s_waitcnt vmcnt(0) lgkmcnt(0)
	s_barrier
	global_load_lds_dwordx4 v[102:103], off
	v_lshl_add_u64 v[102:103], v[98:99], 0, s[24:25]
	v_readfirstlane_b32 s31, v118
	v_lshl_add_u64 v[104:105], v[102:103], 0, s[10:11]
	s_mov_b32 m0, s31
	v_readfirstlane_b32 s31, v119
	global_load_lds_dwordx4 v[104:105], off
	v_lshl_add_u64 v[104:105], v[100:101], 0, s[12:13]
	s_mov_b32 m0, s31
	v_readfirstlane_b32 s31, v120
	global_load_lds_dwordx4 v[104:105], off
	v_lshl_add_u64 v[104:105], v[102:103], 0, s[14:15]
	s_mov_b32 m0, s31
	v_readfirstlane_b32 s31, v121
	global_load_lds_dwordx4 v[104:105], off
	v_lshl_add_u64 v[104:105], v[92:93], 0, s[24:25]
	v_lshl_add_u64 v[106:107], v[104:105], 0, s[4:5]
	s_mov_b32 m0, s31
	v_readfirstlane_b32 s31, v122
	global_load_lds_dwordx4 v[106:107], off
	v_lshl_add_u64 v[106:107], v[94:95], 0, s[24:25]
	v_lshl_add_u64 v[140:141], v[106:107], 0, s[10:11]
	s_mov_b32 m0, s31
	v_readfirstlane_b32 s31, v123
	global_load_lds_dwordx4 v[140:141], off
	v_lshl_add_u64 v[140:141], v[104:105], 0, s[12:13]
	s_mov_b32 m0, s31
	v_readfirstlane_b32 s31, v124
	global_load_lds_dwordx4 v[140:141], off
	v_lshl_add_u64 v[140:141], v[106:107], 0, s[14:15]
	s_mov_b32 m0, s31
	s_nop 0
	global_load_lds_dwordx4 v[140:141], off
	ds_read_b128 v[140:143], v162
	ds_read_b128 v[144:147], v162 offset:2048
	ds_read_b128 v[148:151], v164 offset:16384
	ds_read_b128 v[152:155], v164 offset:18432
	ds_read_b128 v[156:159], v162 offset:4096
	ds_read_b128 v[166:169], v162 offset:6144
	ds_read_b128 v[182:185], v164 offset:20480
	ds_read_b128 v[186:189], v164 offset:22528
	s_setprio 1
	s_waitcnt lgkmcnt(0)
	v_mfma_f32_16x16x32_bf16 v[60:63], v[148:151], v[140:143], v[60:63]
	v_mfma_f32_16x16x32_bf16 v[56:59], v[152:155], v[140:143], v[56:59]
	v_mfma_f32_16x16x32_bf16 v[52:55], v[182:185], v[140:143], v[52:55]
	v_mfma_f32_16x16x32_bf16 v[48:51], v[186:189], v[140:143], v[48:51]
	v_mfma_f32_16x16x32_bf16 v[44:47], v[148:151], v[144:147], v[44:47]
	v_mfma_f32_16x16x32_bf16 v[40:43], v[152:155], v[144:147], v[40:43]
	v_mfma_f32_16x16x32_bf16 v[36:39], v[182:185], v[144:147], v[36:39]
	v_mfma_f32_16x16x32_bf16 v[32:35], v[186:189], v[144:147], v[32:35]
	v_mfma_f32_16x16x32_bf16 v[140:143], v[148:151], v[156:159], v[16:19]
	v_mfma_f32_16x16x32_bf16 v[144:147], v[152:155], v[156:159], v[20:23]
	v_mfma_f32_16x16x32_bf16 v[190:193], v[182:185], v[156:159], v[24:27]
	v_mfma_f32_16x16x32_bf16 v[156:159], v[186:189], v[156:159], v[28:31]
	v_mfma_f32_16x16x32_bf16 v[148:151], v[148:151], v[166:169], v[0:3]
	v_mfma_f32_16x16x32_bf16 v[152:155], v[152:155], v[166:169], v[4:7]
	v_mfma_f32_16x16x32_bf16 v[182:185], v[182:185], v[166:169], v[8:11]
	v_mfma_f32_16x16x32_bf16 v[166:169], v[186:189], v[166:169], v[12:15]
	s_setprio 0
	s_nop 1
	ds_read_b128 v[12:15], v162 offset:1024
	ds_read_b128 v[28:31], v162 offset:3072
	ds_read_b128 v[186:189], v164 offset:17408
	ds_read_b128 v[194:197], v164 offset:19456
	ds_read_b128 v[198:201], v162 offset:5120
	ds_read_b128 v[202:205], v162 offset:7168
	ds_read_b128 v[206:209], v164 offset:21504
	ds_read_b128 v[210:213], v164 offset:23552
	s_setprio 1
	s_waitcnt lgkmcnt(5)
	v_mfma_f32_16x16x32_bf16 v[0:3], v[186:189], v[12:15], v[60:63]
	s_waitcnt lgkmcnt(4)
	v_mfma_f32_16x16x32_bf16 v[4:7], v[194:197], v[12:15], v[56:59]
	s_waitcnt lgkmcnt(1)
	v_mfma_f32_16x16x32_bf16 v[8:11], v[206:209], v[12:15], v[52:55]
	s_waitcnt lgkmcnt(0)
	v_mfma_f32_16x16x32_bf16 v[12:15], v[210:213], v[12:15], v[48:51]
	v_mfma_f32_16x16x32_bf16 v[16:19], v[186:189], v[28:31], v[44:47]
	v_mfma_f32_16x16x32_bf16 v[20:23], v[194:197], v[28:31], v[40:43]
	v_mfma_f32_16x16x32_bf16 v[24:27], v[206:209], v[28:31], v[36:39]
	v_mfma_f32_16x16x32_bf16 v[28:31], v[210:213], v[28:31], v[32:35]
	v_mfma_f32_16x16x32_bf16 v[32:35], v[186:189], v[198:201], v[140:143]
	v_mfma_f32_16x16x32_bf16 v[36:39], v[194:197], v[198:201], v[144:147]
	v_mfma_f32_16x16x32_bf16 v[40:43], v[206:209], v[198:201], v[190:193]
	v_mfma_f32_16x16x32_bf16 v[44:47], v[210:213], v[198:201], v[156:159]
	v_mfma_f32_16x16x32_bf16 v[48:51], v[186:189], v[202:205], v[148:151]
	v_mfma_f32_16x16x32_bf16 v[52:55], v[194:197], v[202:205], v[152:155]
	v_mfma_f32_16x16x32_bf16 v[56:59], v[206:209], v[202:205], v[182:185]
	v_mfma_f32_16x16x32_bf16 v[60:63], v[210:213], v[202:205], v[166:169]
	s_setprio 0
	s_cmpk_eq_i32 s24, 0x700
	s_waitcnt vmcnt(0)
	s_barrier
	s_cbranch_scc1 .LBB0_1040
	v_readfirstlane_b32 s31, v179
	v_lshl_add_u64 v[140:141], v[100:101], 0, s[16:17]
	s_mov_b32 m0, s31
	v_readfirstlane_b32 s31, v110
	global_load_lds_dwordx4 v[140:141], off
	v_lshl_add_u64 v[140:141], v[102:103], 0, s[18:19]
	s_mov_b32 m0, s31
	v_readfirstlane_b32 s31, v111
	global_load_lds_dwordx4 v[140:141], off
	v_lshl_add_u64 v[100:101], v[100:101], 0, s[20:21]
	s_mov_b32 m0, s31
	v_readfirstlane_b32 s31, v112
	global_load_lds_dwordx4 v[100:101], off
	v_lshl_add_u64 v[100:101], v[102:103], 0, s[22:23]
	s_mov_b32 m0, s31
	v_readfirstlane_b32 s31, v113
	global_load_lds_dwordx4 v[100:101], off
	v_lshl_add_u64 v[100:101], v[104:105], 0, s[16:17]
	s_mov_b32 m0, s31
	v_readfirstlane_b32 s31, v114
	global_load_lds_dwordx4 v[100:101], off
	v_lshl_add_u64 v[100:101], v[106:107], 0, s[18:19]
	s_mov_b32 m0, s31
	v_readfirstlane_b32 s31, v115
	global_load_lds_dwordx4 v[100:101], off
	v_lshl_add_u64 v[100:101], v[104:105], 0, s[20:21]
	s_mov_b32 m0, s31
	v_readfirstlane_b32 s31, v116
	global_load_lds_dwordx4 v[100:101], off
	v_lshl_add_u64 v[100:101], v[106:107], 0, s[22:23]
	s_mov_b32 m0, s31
	s_nop 0
	global_load_lds_dwordx4 v[100:101], off
	s_branch .LBB0_1040
